# attention task remap (8 heads per workgroup), conv_local loads pipelined 4 rows ahead with counted vmcnt, pass1/pass2 store drains off the loop-top wait, epilogue load hoists
# speedup vs baseline: 1.0479x; 1.0270x over previous
; __device__ __forceinline__ unsigned pk2(float lo, float hi) { return pg8::cvt_pk_bf16(lo, hi); }
; __device__ __forceinline__ float silu_f(float x) { return x * sigmoid_f(x); }
; __device__ __forceinline__ void conv_local(const bf16_t* PR, const float* cw, const float* cb, bf16_t* QC, bf16_t* KC, int st) {
;     ...
;         const int R0 = b * SEQL + seg * 512 + rrange * 32; const bool first = (R0 & (SEQL - 1)) == 0;
;         float x1[8], x2[8], x3[8];
;         { const bf16_t* src = PR + (size_t)R0 * PW + PC_QM + c8;
;           u32x4 a1 = {0u, 0u, 0u, 0u}, a2 = a1, a3 = a1;
;           if (!first) { a1 = *(const u32x4*)(src - PW); a2 = *(const u32x4*)(src - 2 * PW); a3 = *(const u32x4*)(src - 3 * PW); }
; #pragma unroll
;           for (int e = 0; e < 4; ++e) { x1[2 * e] = __uint_as_float(a1[e] << 16); x1[2 * e + 1] = __uint_as_float(a1[e] & 0xffff0000u);
;               x2[2 * e] = __uint_as_float(a2[e] << 16); x2[2 * e + 1] = __uint_as_float(a2[e] & 0xffff0000u);
;               x3[2 * e] = __uint_as_float(a3[e] << 16); x3[2 * e + 1] = __uint_as_float(a3[e] & 0xffff0000u); } }
; #pragma unroll 4
;         for (int i = 0; i < 32; ++i) {
;             const u32x4 xv = *(const u32x4*)(PR + (size_t)(R0 + i) * PW + PC_QM + c8);
;             float x0[8];
; #pragma unroll
;             for (int e = 0; e < 4; ++e) { x0[2 * e] = __uint_as_float(xv[e] << 16); x0[2 * e + 1] = __uint_as_float(xv[e] & 0xffff0000u); }
;             u32x4 o;
; #pragma unroll
;             for (int e = 0; e < 4; ++e) {
;                 const float v0 = bias[2 * e] + wgt[0][2 * e] * x3[2 * e] + wgt[1][2 * e] * x2[2 * e] + wgt[2][2 * e] * x1[2 * e] + wgt[3][2 * e] * x0[2 * e];
;                 const float v1 = bias[2 * e + 1] + wgt[0][2 * e + 1] * x3[2 * e + 1] + wgt[1][2 * e + 1] * x2[2 * e + 1] + wgt[2][2 * e + 1] * x1[2 * e + 1] + wgt[3][2 * e + 1] * x0[2 * e + 1];
;                 o[e] = pk2(silu_f(v0) * sc, silu_f(v1) * sc); }
;             *(u32x4*)(dst0 + (size_t)(R0 + i) * 512) = o;
; #pragma unroll
;             for (int e = 0; e < 8; ++e) { x3[e] = x2[e]; x2[e] = x1[e]; x1[e] = x0[e]; }
;         }
.LBB0_453:
	s_or_b64 exec, exec, s[0:1]
	v_readlane_b32 s0, v235, 60
	s_and_b32 s2, s0, 0xfffff800
	v_readlane_b32 s0, v235, 13
	s_and_b32 s3, s0, 0x600
	v_readlane_b32 s0, v235, 46
	v_readlane_b32 s1, v235, 47
	v_cmp_lt_u32_e32 vcc, s74, v52
	s_waitcnt vmcnt(0) lgkmcnt(0)
	v_lshlrev_b32_e32 v62, 16, v40
	v_lshl_add_u64 v[52:53], s[0:1], 0, v[136:137]
	s_movk_i32 s0, 0xfc00
	s_mov_b32 s1, -1
	v_lshl_add_u64 v[52:53], v[52:53], 0, s[0:1]
	v_readlane_b32 s0, v235, 44
	v_readlane_b32 s1, v235, 45
	v_and_b32_e32 v64, 0xffff0000, v40
	v_lshlrev_b32_e32 v66, 16, v41
	v_lshl_add_u64 v[54:55], s[0:1], 0, v[136:137]
	s_or_b32 s0, s2, s3
	v_add_u32_e32 v58, s0, v58
	v_ashrrev_i32_e32 v59, 31, v58
	v_cndmask_b32_e32 v61, v55, v53, vcc
	v_cndmask_b32_e32 v60, v54, v52, vcc
	v_lshlrev_b32_e32 v52, 16, v44
	v_and_b32_e32 v54, 0xffff0000, v44
	v_lshlrev_b32_e32 v53, 16, v48
	v_and_b32_e32 v55, 0xffff0000, v48
	v_and_b32_e32 v68, 0xffff0000, v41
	v_lshlrev_b32_e32 v40, 16, v45
	v_and_b32_e32 v44, 0xffff0000, v45
	v_lshlrev_b32_e32 v41, 16, v49
	v_and_b32_e32 v45, 0xffff0000, v49
	v_lshlrev_b32_e32 v70, 16, v42
	v_and_b32_e32 v72, 0xffff0000, v42
	v_lshlrev_b32_e32 v48, 16, v46
	v_and_b32_e32 v56, 0xffff0000, v46
	v_lshlrev_b32_e32 v49, 16, v50
	v_and_b32_e32 v57, 0xffff0000, v50
	v_lshlrev_b32_e32 v74, 16, v43
	v_and_b32_e32 v76, 0xffff0000, v43
	v_lshlrev_b32_e32 v42, 16, v47
	v_and_b32_e32 v46, 0xffff0000, v47
	v_lshlrev_b32_e32 v43, 16, v51
	v_and_b32_e32 v47, 0xffff0000, v51
	v_mov_b32_e32 v50, v38
	v_mov_b32_e32 v51, v6
	v_mov_b32_e32 v6, v39
	v_mov_b32_e32 v38, v34
	v_mov_b32_e32 v39, v10
	v_mov_b32_e32 v10, v35
	v_mov_b32_e32 v34, v36
	v_mov_b32_e32 v35, v4
	v_mov_b32_e32 v4, v37
	v_mov_b32_e32 v36, v32
	v_mov_b32_e32 v37, v8
	v_mov_b32_e32 v8, v33
	v_mov_b32_e32 v32, v30
	v_mov_b32_e32 v33, v2
	v_mov_b32_e32 v2, v31
	v_mov_b32_e32 v30, v26
	v_mov_b32_e32 v31, v18
	v_mov_b32_e32 v18, v27
	v_mov_b32_e32 v26, v28
	v_mov_b32_e32 v27, v0
	v_mov_b32_e32 v0, v29
	v_mov_b32_e32 v28, v24
	v_mov_b32_e32 v29, v16
	v_mov_b32_e32 v16, v25
	v_lshlrev_b64 v[24:25], 10, v[58:59]
	v_mad_i64_i32 v[58:59], s[0:1], v58, s79, v[136:137]
	v_readlane_b32 s0, v235, 62
	v_readlane_b32 s1, v235, 63
	v_cndmask_b32_e32 v112, 1.0, v141, vcc
	v_lshl_add_u64 v[24:25], v[60:61], 0, v[24:25]
	v_lshl_add_u64 v[58:59], s[0:1], 0, v[58:59]
	s_mov_b64 s[4:5], 0
	s_mov_b64 s[98:99], 0x1c00
	s_mov_b32 s100, 0xffffac00
	s_mov_b32 s101, -1
	v_lshl_add_u64 v[252:253], v[58:59], 0, s[100:101]
	global_load_dwordx4 v[236:239], v[252:253], off
	v_lshl_add_u64 v[252:253], v[252:253], 0, s[98:99]
	global_load_dwordx4 v[240:243], v[252:253], off
	v_lshl_add_u64 v[252:253], v[252:253], 0, s[98:99]
	global_load_dwordx4 v[244:247], v[252:253], off
	v_lshl_add_u64 v[252:253], v[252:253], 0, s[98:99]
	global_load_dwordx4 v[248:251], v[252:253], off
	v_lshl_add_u64 v[252:253], v[252:253], 0, s[98:99]
	s_waitcnt vmcnt(0)
.LBB0_454:
	s_movk_i32 s2, 0xac00
	v_pk_mul_f32 v[90:91], v[38:39], v[42:43]
	v_pk_mul_f32 v[92:93], v[10:11], v[46:47]
	v_mov_b32_e32 v43, v46
	v_add_co_u32_e32 v46, vcc, s2, v58
	v_pk_mul_f32 v[80:81], v[16:17], v[54:55]
	v_pk_mul_f32 v[82:83], v[30:31], v[40:41]
	v_pk_mul_f32 v[88:89], v[8:9], v[56:57]
	v_mov_b32_e32 v55, v40
	v_mov_b32_e32 v40, v68
	v_mov_b32_e32 v41, v44
	v_mov_b32_e32 v57, v42
	v_mov_b32_e32 v42, v76
	v_addc_co_u32_e32 v47, vcc, -1, v59, vcc
	v_pk_mul_f32 v[118:119], v[18:19], v[40:41]
	v_pk_mul_f32 v[120:121], v[10:11], v[42:43]
	s_nop 0
	v_pk_mul_f32 v[78:79], v[28:29], v[52:53]
	v_pk_mul_f32 v[84:85], v[18:19], v[44:45]
	v_pk_mul_f32 v[86:87], v[36:37], v[48:49]
	v_add_f32_e32 v63, v20, v79
	v_add_f32_e32 v65, v21, v81
	v_mov_b32_e32 v95, v52
	v_mov_b32_e32 v52, v64
	v_mov_b32_e32 v53, v54
	v_mov_b32_e32 v54, v66
	v_mov_b32_e32 v44, v70
	v_mov_b32_e32 v45, v48
	v_mov_b32_e32 v48, v72
	v_mov_b32_e32 v49, v56
	v_mov_b32_e32 v56, v74
	v_add_f32_e32 v67, v22, v83
	v_add_f32_e32 v69, v23, v85
	v_add_f32_e32 v71, v12, v87
	v_add_f32_e32 v73, v13, v89
	v_add_f32_e32 v75, v14, v91
	v_add_f32_e32 v77, v15, v93
	v_add_f32_e32 v47, v78, v63
	v_add_f32_e32 v113, v80, v65
	v_add_f32_e32 v63, v23, v119
	v_add_f32_e32 v65, v15, v121
	v_mov_b32_e32 v94, v62
	v_pk_mul_f32 v[52:53], v[16:17], v[52:53]
	v_pk_mul_f32 v[54:55], v[30:31], v[54:55]
	v_pk_mul_f32 v[44:45], v[36:37], v[44:45]
	v_pk_mul_f32 v[48:49], v[8:9], v[48:49]
	v_pk_mul_f32 v[56:57], v[38:39], v[56:57]
	v_add_f32_e32 v122, v82, v67
	v_add_f32_e32 v123, v84, v69
	v_add_f32_e32 v124, v86, v71
	v_add_f32_e32 v125, v88, v73
	v_add_f32_e32 v126, v90, v75
	v_add_f32_e32 v127, v92, v77
	v_add_f32_e32 v118, v118, v63
	v_add_f32_e32 v132, v120, v65
	v_pk_mul_f32 v[116:117], v[28:29], v[94:95]
	v_add_f32_e32 v53, v21, v53
	v_add_f32_e32 v55, v22, v55
	v_add_f32_e32 v45, v12, v45
	v_add_f32_e32 v49, v13, v49
	v_add_f32_e32 v57, v14, v57
	v_mov_b32_e32 v97, v62
	v_mov_b32_e32 v99, v64
	v_mov_b32_e32 v101, v66
	v_mov_b32_e32 v103, v68
	v_mov_b32_e32 v105, v70
	v_mov_b32_e32 v107, v72
	v_mov_b32_e32 v109, v74
	v_mov_b32_e32 v111, v76
	v_add_f32_e32 v46, v20, v117
	v_add_f32_e32 v117, v52, v53
	v_add_f32_e32 v128, v54, v55
	v_add_f32_e32 v129, v44, v45
	v_add_f32_e32 v130, v48, v49
	v_add_f32_e32 v131, v56, v57
	s_movk_i32 s3, 0xc800
	v_lshl_add_u64 v[60:61], v[24:25], 0, s[4:5]
	v_add_co_u32_e32 v114, vcc, s3, v58
	v_add_f32_e32 v116, v116, v46
	s_nop 0
	v_addc_co_u32_e32 v115, vcc, -1, v59, vcc
	s_movk_i32 s6, 0xe400
	v_add_co_u32_e32 v94, vcc, s6, v58
	s_add_u32 s4, s4, 0x1000
	s_nop 0
	v_addc_co_u32_e32 v95, vcc, -1, v59, vcc
	s_mov_b64 s[0:1], 0x7000
	s_addc_u32 s5, s5, 0
	s_cmpk_lg_u32 s4, 0x8000
	s_waitcnt vmcnt(7) lgkmcnt(0)
; __device__ __forceinline__ unsigned pk2(float lo, float hi) { return pg8::cvt_pk_bf16(lo, hi); }
; __device__ __forceinline__ float silu_f(float x) { return x * sigmoid_f(x); }
; __device__ __forceinline__ void conv_local(const bf16_t* PR, const float* cw, const float* cb, bf16_t* QC, bf16_t* KC, int st) {
;     ...
;         for (int i = 0; i < 32; ++i) {
;             const u32x4 xv = *(const u32x4*)(PR + (size_t)(R0 + i) * PW + PC_QM + c8);
;             float x0[8];
; #pragma unroll
;             for (int e = 0; e < 4; ++e) { x0[2 * e] = __uint_as_float(xv[e] << 16); x0[2 * e + 1] = __uint_as_float(xv[e] & 0xffff0000u); }
;             u32x4 o;
; #pragma unroll
;             for (int e = 0; e < 4; ++e) {
;                 const float v0 = bias[2 * e] + wgt[0][2 * e] * x3[2 * e] + wgt[1][2 * e] * x2[2 * e] + wgt[2][2 * e] * x1[2 * e] + wgt[3][2 * e] * x0[2 * e];
;                 const float v1 = bias[2 * e + 1] + wgt[0][2 * e + 1] * x3[2 * e + 1] + wgt[1][2 * e + 1] * x2[2 * e + 1] + wgt[2][2 * e + 1] * x1[2 * e + 1] + wgt[3][2 * e + 1] * x0[2 * e + 1];
;                 o[e] = pk2(silu_f(v0) * sc, silu_f(v1) * sc); }
;             *(u32x4*)(dst0 + (size_t)(R0 + i) * 512) = o;
; #pragma unroll
;             for (int e = 0; e < 8; ++e) { x3[e] = x2[e]; x2[e] = x1[e]; x1[e] = x0[e]; }
;         }
	v_mov_b32_e32 v40, v236
	v_mov_b32_e32 v41, v237
	v_mov_b32_e32 v42, v238
	v_mov_b32_e32 v43, v239
	global_load_dwordx4 v[236:239], v[252:253], off
	v_lshl_add_u64 v[252:253], v[252:253], 0, s[98:99]
	v_lshlrev_b32_e32 v63, 16, v40
	v_and_b32_e32 v65, 0xffff0000, v40
	v_lshlrev_b32_e32 v67, 16, v41
	v_and_b32_e32 v69, 0xffff0000, v41
	v_lshlrev_b32_e32 v71, 16, v42
	v_and_b32_e32 v73, 0xffff0000, v42
	v_lshlrev_b32_e32 v75, 16, v43
	v_and_b32_e32 v77, 0xffff0000, v43
	v_pk_mul_f32 v[78:79], v[26:27], v[62:63]
	v_pk_mul_f32 v[80:81], v[0:1], v[64:65]
	v_pk_mul_f32 v[82:83], v[32:33], v[66:67]
	v_pk_mul_f32 v[84:85], v[2:3], v[68:69]
	v_pk_mul_f32 v[86:87], v[34:35], v[70:71]
	v_pk_mul_f32 v[88:89], v[4:5], v[72:73]
	v_pk_mul_f32 v[90:91], v[50:51], v[74:75]
	v_pk_mul_f32 v[92:93], v[6:7], v[76:77]
	v_mov_b32_e32 v96, v63
	v_mov_b32_e32 v98, v65
	v_mov_b32_e32 v100, v67
	v_mov_b32_e32 v102, v69
	v_mov_b32_e32 v104, v71
	v_mov_b32_e32 v106, v73
	v_mov_b32_e32 v108, v75
	v_mov_b32_e32 v110, v77
	v_add_f32_e32 v41, v78, v47
	v_add_f32_e32 v43, v80, v113
	v_add_f32_e32 v45, v82, v122
	v_add_f32_e32 v47, v84, v123
	v_add_f32_e32 v49, v86, v124
	v_add_f32_e32 v53, v88, v125
	v_add_f32_e32 v55, v90, v126
	v_add_f32_e32 v57, v92, v127
	v_pk_mul_f32 v[96:97], v[28:29], v[96:97]
	v_pk_mul_f32 v[98:99], v[16:17], v[98:99]
	v_pk_mul_f32 v[100:101], v[30:31], v[100:101]
	v_pk_mul_f32 v[102:103], v[18:19], v[102:103]
	v_pk_mul_f32 v[104:105], v[36:37], v[104:105]
	v_pk_mul_f32 v[106:107], v[8:9], v[106:107]
	v_pk_mul_f32 v[108:109], v[38:39], v[108:109]
	v_pk_mul_f32 v[110:111], v[10:11], v[110:111]
	v_add_f32_e32 v41, v41, v79
	v_add_f32_e32 v43, v43, v81
	v_add_f32_e32 v45, v45, v83
	v_add_f32_e32 v47, v47, v85
	v_add_f32_e32 v49, v49, v87
	v_add_f32_e32 v53, v53, v89
	v_add_f32_e32 v55, v55, v91
	v_add_f32_e32 v57, v57, v93
	v_add_f32_e32 v62, v20, v97
	v_add_f32_e32 v64, v21, v99
	v_add_f32_e32 v66, v22, v101
	v_add_f32_e32 v68, v23, v103
	v_add_f32_e32 v70, v12, v105
	v_add_f32_e32 v72, v13, v107
	v_add_f32_e32 v74, v14, v109
	v_add_f32_e32 v76, v15, v111
	v_mul_f32_e32 v78, 0xbfb8aa3b, v41
	v_mul_f32_e32 v79, 0xbfb8aa3b, v43
	v_mul_f32_e32 v80, 0xbfb8aa3b, v45
	v_mul_f32_e32 v81, 0xbfb8aa3b, v47
	v_mul_f32_e32 v82, 0xbfb8aa3b, v49
	v_mul_f32_e32 v83, 0xbfb8aa3b, v53
	v_mul_f32_e32 v84, 0xbfb8aa3b, v55
	v_mul_f32_e32 v85, 0xbfb8aa3b, v57
	v_add_f32_e32 v119, v96, v62
	v_add_f32_e32 v120, v98, v64
	v_add_f32_e32 v121, v100, v66
	v_add_f32_e32 v122, v102, v68
	v_add_f32_e32 v123, v104, v70
	v_add_f32_e32 v124, v106, v72
	v_add_f32_e32 v125, v108, v74
	v_add_f32_e32 v126, v110, v76
	v_exp_f32_e32 v62, v78
	v_exp_f32_e32 v64, v79
	v_exp_f32_e32 v66, v80
	v_exp_f32_e32 v68, v81
	v_exp_f32_e32 v70, v82
	v_exp_f32_e32 v72, v83
	v_exp_f32_e32 v74, v84
	v_exp_f32_e32 v76, v85
	v_add_f32_e32 v62, 1.0, v62
	v_add_f32_e32 v64, 1.0, v64
	v_add_f32_e32 v66, 1.0, v66
	v_add_f32_e32 v68, 1.0, v68
	v_add_f32_e32 v70, 1.0, v70
	v_add_f32_e32 v72, 1.0, v72
	v_add_f32_e32 v74, 1.0, v74
	v_add_f32_e32 v76, 1.0, v76
	v_rcp_f32_e32 v62, v62
	v_rcp_f32_e32 v64, v64
	v_rcp_f32_e32 v66, v66
	v_rcp_f32_e32 v68, v68
	v_rcp_f32_e32 v70, v70
	v_rcp_f32_e32 v72, v72
	v_rcp_f32_e32 v74, v74
	v_rcp_f32_e32 v76, v76
	v_mul_f32_e32 v41, v41, v62
	v_mul_f32_e32 v43, v43, v64
	v_mul_f32_e32 v45, v45, v66
	v_mul_f32_e32 v47, v47, v68
	v_mul_f32_e32 v49, v49, v70
	v_mul_f32_e32 v53, v53, v72
	v_mul_f32_e32 v55, v55, v74
	v_mul_f32_e32 v57, v57, v76
	v_mul_f32_e32 v41, v112, v41
	v_mul_f32_e32 v43, v112, v43
	v_mul_f32_e32 v45, v112, v45
	v_mul_f32_e32 v47, v112, v47
	v_mul_f32_e32 v49, v112, v49
	v_mul_f32_e32 v53, v112, v53
	v_mul_f32_e32 v55, v112, v55
	v_mul_f32_e32 v57, v112, v57
	v_cvt_pk_bf16_f32 v78, v41, v43
	v_cvt_pk_bf16_f32 v79, v45, v47
	v_cvt_pk_bf16_f32 v80, v49, v53
	v_cvt_pk_bf16_f32 v81, v55, v57
	global_store_dwordx4 v[60:61], v[78:81], off
	s_nop 0
	v_mov_b32_e32 v52, v63
	v_mov_b32_e32 v54, v65
	v_mov_b32_e32 v40, v67
	v_mov_b32_e32 v44, v69
	v_mov_b32_e32 v48, v71
	v_mov_b32_e32 v56, v73
	v_mov_b32_e32 v42, v75
	v_mov_b32_e32 v46, v77
	s_waitcnt vmcnt(7) lgkmcnt(0)
	v_mov_b32_e32 v78, v240
	v_mov_b32_e32 v79, v241
	v_mov_b32_e32 v80, v242
	v_mov_b32_e32 v81, v243
	global_load_dwordx4 v[240:243], v[252:253], off
	v_lshl_add_u64 v[252:253], v[252:253], 0, s[98:99]
	v_lshlrev_b32_e32 v53, 16, v78
	v_and_b32_e32 v55, 0xffff0000, v78
	v_lshlrev_b32_e32 v41, 16, v79
	v_and_b32_e32 v45, 0xffff0000, v79
	v_lshlrev_b32_e32 v49, 16, v80
	v_and_b32_e32 v57, 0xffff0000, v80
	v_lshlrev_b32_e32 v43, 16, v81
	v_and_b32_e32 v47, 0xffff0000, v81
	v_pk_mul_f32 v[96:97], v[26:27], v[52:53]
	v_pk_mul_f32 v[98:99], v[0:1], v[54:55]
	v_pk_mul_f32 v[100:101], v[32:33], v[40:41]
	v_pk_mul_f32 v[102:103], v[2:3], v[44:45]
	v_pk_mul_f32 v[104:105], v[34:35], v[48:49]
	v_pk_mul_f32 v[106:107], v[4:5], v[56:57]
	v_pk_mul_f32 v[108:109], v[50:51], v[42:43]
	v_pk_mul_f32 v[110:111], v[6:7], v[46:47]
	v_mov_b32_e32 v62, v53
	v_mov_b32_e32 v64, v55
	v_mov_b32_e32 v66, v41
	v_mov_b32_e32 v68, v45
	v_add_f32_e32 v40, v96, v116
	v_add_f32_e32 v42, v98, v117
	v_add_f32_e32 v44, v100, v128
	v_add_f32_e32 v46, v102, v118
	v_add_f32_e32 v48, v104, v129
	v_add_f32_e32 v52, v106, v130
	v_add_f32_e32 v54, v108, v131
	v_add_f32_e32 v56, v110, v132
	v_pk_mul_f32 v[62:63], v[28:29], v[62:63]
	v_pk_mul_f32 v[64:65], v[16:17], v[64:65]
	v_pk_mul_f32 v[66:67], v[30:31], v[66:67]
	v_pk_mul_f32 v[68:69], v[18:19], v[68:69]
	v_add_f32_e32 v40, v40, v97
	v_add_f32_e32 v42, v42, v99
	v_add_f32_e32 v44, v44, v101
	v_add_f32_e32 v46, v46, v103
	v_add_f32_e32 v48, v48, v105
	v_add_f32_e32 v52, v52, v107
; __device__ __forceinline__ unsigned pk2(float lo, float hi) { return pg8::cvt_pk_bf16(lo, hi); }
; __device__ __forceinline__ float silu_f(float x) { return x * sigmoid_f(x); }
; __device__ __forceinline__ void conv_local(const bf16_t* PR, const float* cw, const float* cb, bf16_t* QC, bf16_t* KC, int st) {
;     ...
;         for (int i = 0; i < 32; ++i) {
;             const u32x4 xv = *(const u32x4*)(PR + (size_t)(R0 + i) * PW + PC_QM + c8);
;             float x0[8];
; #pragma unroll
;             for (int e = 0; e < 4; ++e) { x0[2 * e] = __uint_as_float(xv[e] << 16); x0[2 * e + 1] = __uint_as_float(xv[e] & 0xffff0000u); }
;             u32x4 o;
; #pragma unroll
;             for (int e = 0; e < 4; ++e) {
;                 const float v0 = bias[2 * e] + wgt[0][2 * e] * x3[2 * e] + wgt[1][2 * e] * x2[2 * e] + wgt[2][2 * e] * x1[2 * e] + wgt[3][2 * e] * x0[2 * e];
;                 const float v1 = bias[2 * e + 1] + wgt[0][2 * e + 1] * x3[2 * e + 1] + wgt[1][2 * e + 1] * x2[2 * e + 1] + wgt[2][2 * e + 1] * x1[2 * e + 1] + wgt[3][2 * e + 1] * x0[2 * e + 1];
;                 o[e] = pk2(silu_f(v0) * sc, silu_f(v1) * sc); }
;             *(u32x4*)(dst0 + (size_t)(R0 + i) * 512) = o;
; #pragma unroll
;             for (int e = 0; e < 8; ++e) { x3[e] = x2[e]; x2[e] = x1[e]; x1[e] = x0[e]; }
;         }
	v_add_f32_e32 v54, v54, v109
	v_add_f32_e32 v56, v56, v111
	v_add_f32_e32 v63, v20, v63
	v_add_f32_e32 v65, v21, v65
	v_add_f32_e32 v67, v22, v67
	v_add_f32_e32 v69, v23, v69
	v_mul_f32_e32 v79, 0xbfb8aa3b, v40
	v_mul_f32_e32 v81, 0xbfb8aa3b, v42
	v_mul_f32_e32 v83, 0xbfb8aa3b, v44
	v_mul_f32_e32 v85, 0xbfb8aa3b, v46
	v_mul_f32_e32 v87, 0xbfb8aa3b, v48
	v_mul_f32_e32 v89, 0xbfb8aa3b, v52
	v_mul_f32_e32 v91, 0xbfb8aa3b, v54
	v_mul_f32_e32 v93, 0xbfb8aa3b, v56
	v_add_f32_e32 v110, v62, v63
	v_add_f32_e32 v111, v64, v65
	v_add_f32_e32 v113, v66, v67
	v_add_f32_e32 v114, v68, v69
	v_exp_f32_e32 v62, v79
	v_exp_f32_e32 v63, v81
	v_exp_f32_e32 v64, v83
	v_exp_f32_e32 v65, v85
	v_exp_f32_e32 v66, v87
	v_exp_f32_e32 v67, v89
	v_exp_f32_e32 v68, v91
	v_exp_f32_e32 v69, v93
	v_add_f32_e32 v62, 1.0, v62
	v_add_f32_e32 v63, 1.0, v63
	v_add_f32_e32 v64, 1.0, v64
	v_add_f32_e32 v65, 1.0, v65
	v_add_f32_e32 v66, 1.0, v66
	v_add_f32_e32 v67, 1.0, v67
	v_add_f32_e32 v68, 1.0, v68
	v_add_f32_e32 v69, 1.0, v69
	v_rcp_f32_e32 v62, v62
	v_rcp_f32_e32 v63, v63
	v_rcp_f32_e32 v64, v64
	v_rcp_f32_e32 v65, v65
	v_rcp_f32_e32 v66, v66
	v_rcp_f32_e32 v67, v67
	v_rcp_f32_e32 v68, v68
	v_rcp_f32_e32 v69, v69
	v_mul_f32_e32 v40, v40, v62
	v_mul_f32_e32 v42, v42, v63
	v_mul_f32_e32 v44, v44, v64
	v_mul_f32_e32 v46, v46, v65
	v_mul_f32_e32 v48, v48, v66
	v_mul_f32_e32 v52, v52, v67
	v_mul_f32_e32 v54, v54, v68
	v_mul_f32_e32 v56, v56, v69
	v_mul_f32_e32 v40, v112, v40
	v_mul_f32_e32 v42, v112, v42
	v_mul_f32_e32 v44, v112, v44
	v_mul_f32_e32 v46, v112, v46
	v_mul_f32_e32 v48, v112, v48
	v_mul_f32_e32 v52, v112, v52
	v_mul_f32_e32 v54, v112, v54
	v_mul_f32_e32 v56, v112, v56
	v_cvt_pk_bf16_f32 v62, v40, v42
	v_cvt_pk_bf16_f32 v63, v44, v46
	v_cvt_pk_bf16_f32 v64, v48, v52
	v_cvt_pk_bf16_f32 v65, v54, v56
	global_store_dwordx4 v[60:61], v[62:65], off offset:1024
	s_nop 0
	v_mov_b32_e32 v70, v49
	v_mov_b32_e32 v92, v53
	v_mov_b32_e32 v90, v55
	v_mov_b32_e32 v88, v41
	v_mov_b32_e32 v86, v45
	v_mov_b32_e32 v84, v49
	v_mov_b32_e32 v82, v57
	v_mov_b32_e32 v80, v43
	v_mov_b32_e32 v78, v47
	v_pk_mul_f32 v[70:71], v[36:37], v[70:71]
	v_mov_b32_e32 v72, v57
	v_mov_b32_e32 v74, v43
	v_mov_b32_e32 v76, v47
	v_add_f32_e32 v71, v12, v71
	v_pk_mul_f32 v[72:73], v[8:9], v[72:73]
	v_pk_mul_f32 v[74:75], v[38:39], v[74:75]
	v_pk_mul_f32 v[76:77], v[10:11], v[76:77]
	v_add_f32_e32 v115, v70, v71
	v_add_f32_e32 v73, v13, v73
	v_add_f32_e32 v75, v14, v75
	v_add_f32_e32 v77, v15, v77
	v_add_f32_e32 v116, v72, v73
	v_add_f32_e32 v117, v74, v75
	v_add_f32_e32 v118, v76, v77
	s_waitcnt vmcnt(7) lgkmcnt(0)
	v_mov_b32_e32 v62, v244
	v_mov_b32_e32 v63, v245
	v_mov_b32_e32 v64, v246
	v_mov_b32_e32 v65, v247
	global_load_dwordx4 v[244:247], v[252:253], off
	v_lshl_add_u64 v[252:253], v[252:253], 0, s[98:99]
	v_lshlrev_b32_e32 v93, 16, v62
	v_and_b32_e32 v91, 0xffff0000, v62
	v_lshlrev_b32_e32 v89, 16, v63
	v_and_b32_e32 v87, 0xffff0000, v63
	v_lshlrev_b32_e32 v85, 16, v64
	v_and_b32_e32 v83, 0xffff0000, v64
	v_lshlrev_b32_e32 v81, 16, v65
	v_and_b32_e32 v79, 0xffff0000, v65
	v_pk_mul_f32 v[94:95], v[26:27], v[92:93]
	v_pk_mul_f32 v[96:97], v[0:1], v[90:91]
	v_pk_mul_f32 v[98:99], v[32:33], v[88:89]
	v_pk_mul_f32 v[100:101], v[2:3], v[86:87]
	v_pk_mul_f32 v[102:103], v[34:35], v[84:85]
	v_pk_mul_f32 v[104:105], v[4:5], v[82:83]
	v_pk_mul_f32 v[106:107], v[50:51], v[80:81]
	v_pk_mul_f32 v[108:109], v[6:7], v[78:79]
	v_add_f32_e32 v42, v94, v119
	v_add_f32_e32 v46, v96, v120
	v_add_f32_e32 v56, v98, v121
	v_add_f32_e32 v63, v100, v122
	v_add_f32_e32 v65, v102, v123
	v_add_f32_e32 v67, v104, v124
	v_add_f32_e32 v69, v106, v125
	v_add_f32_e32 v71, v108, v126
	v_add_f32_e32 v42, v42, v95
	v_add_f32_e32 v46, v46, v97
	v_add_f32_e32 v56, v56, v99
	v_add_f32_e32 v63, v63, v101
	v_add_f32_e32 v65, v65, v103
	v_add_f32_e32 v67, v67, v105
	v_add_f32_e32 v69, v69, v107
	v_add_f32_e32 v71, v71, v109
	v_mov_b32_e32 v68, v85
	v_mov_b32_e32 v48, v85
	v_mul_f32_e32 v73, 0xbfb8aa3b, v42
	v_mul_f32_e32 v75, 0xbfb8aa3b, v46
	v_mul_f32_e32 v77, 0xbfb8aa3b, v56
	v_mul_f32_e32 v78, 0xbfb8aa3b, v63
	v_mul_f32_e32 v80, 0xbfb8aa3b, v65
	v_mul_f32_e32 v82, 0xbfb8aa3b, v67
	v_mul_f32_e32 v84, 0xbfb8aa3b, v69
	v_mul_f32_e32 v85, 0xbfb8aa3b, v71
	v_exp_f32_e32 v73, v73
	v_exp_f32_e32 v75, v75
	v_exp_f32_e32 v77, v77
	v_exp_f32_e32 v78, v78
	v_exp_f32_e32 v80, v80
	v_exp_f32_e32 v82, v82
	v_exp_f32_e32 v84, v84
	v_exp_f32_e32 v85, v85
	v_add_f32_e32 v73, 1.0, v73
	v_add_f32_e32 v75, 1.0, v75
	v_add_f32_e32 v77, 1.0, v77
	v_add_f32_e32 v78, 1.0, v78
	v_add_f32_e32 v80, 1.0, v80
	v_add_f32_e32 v82, 1.0, v82
	v_add_f32_e32 v84, 1.0, v84
	v_add_f32_e32 v85, 1.0, v85
	v_rcp_f32_e32 v73, v73
	v_rcp_f32_e32 v75, v75
	v_rcp_f32_e32 v77, v77
	v_rcp_f32_e32 v78, v78
	v_rcp_f32_e32 v80, v80
	v_rcp_f32_e32 v82, v82
	v_rcp_f32_e32 v84, v84
	v_rcp_f32_e32 v85, v85
	v_mul_f32_e32 v42, v42, v73
	v_mul_f32_e32 v46, v46, v75
	v_mul_f32_e32 v56, v56, v77
	v_mul_f32_e32 v63, v63, v78
	v_mul_f32_e32 v65, v65, v80
	v_mul_f32_e32 v67, v67, v82
	v_mul_f32_e32 v69, v69, v84
	v_mul_f32_e32 v71, v71, v85
	v_mov_b32_e32 v70, v87
	v_mov_b32_e32 v44, v87
	v_mul_f32_e32 v42, v112, v42
	v_mul_f32_e32 v46, v112, v46
	v_mul_f32_e32 v56, v112, v56
	v_mul_f32_e32 v63, v112, v63
	v_mul_f32_e32 v65, v112, v65
	v_mul_f32_e32 v67, v112, v67
	v_mul_f32_e32 v69, v112, v69
	v_mul_f32_e32 v71, v112, v71
	v_cvt_pk_bf16_f32 v84, v42, v46
	v_cvt_pk_bf16_f32 v85, v56, v63
	v_cvt_pk_bf16_f32 v86, v65, v67
	v_cvt_pk_bf16_f32 v87, v69, v71
	global_store_dwordx4 v[60:61], v[84:87], off offset:2048
	s_nop 0
	v_mov_b32_e32 v76, v93
	v_mov_b32_e32 v74, v91
	v_mov_b32_e32 v72, v89
	v_mov_b32_e32 v66, v83
	v_mov_b32_e32 v64, v81
	v_mov_b32_e32 v62, v79
	v_mov_b32_e32 v52, v93
	v_mov_b32_e32 v54, v91
	v_mov_b32_e32 v40, v89
	v_mov_b32_e32 v56, v83
	v_mov_b32_e32 v42, v81
	v_mov_b32_e32 v46, v79
	v_lshl_add_u64 v[58:59], v[58:59], 0, s[0:1]
	s_waitcnt vmcnt(7) lgkmcnt(0)
; __device__ __forceinline__ unsigned pk2(float lo, float hi) { return pg8::cvt_pk_bf16(lo, hi); }
; __device__ __forceinline__ float silu_f(float x) { return x * sigmoid_f(x); }
; __device__ __forceinline__ void conv_local(const bf16_t* PR, const float* cw, const float* cb, bf16_t* QC, bf16_t* KC, int st) {
;     ...
;         for (int i = 0; i < 32; ++i) {
;             const u32x4 xv = *(const u32x4*)(PR + (size_t)(R0 + i) * PW + PC_QM + c8);
;             float x0[8];
; #pragma unroll
;             for (int e = 0; e < 4; ++e) { x0[2 * e] = __uint_as_float(xv[e] << 16); x0[2 * e + 1] = __uint_as_float(xv[e] & 0xffff0000u); }
;             u32x4 o;
; #pragma unroll
;             for (int e = 0; e < 4; ++e) {
;                 const float v0 = bias[2 * e] + wgt[0][2 * e] * x3[2 * e] + wgt[1][2 * e] * x2[2 * e] + wgt[2][2 * e] * x1[2 * e] + wgt[3][2 * e] * x0[2 * e];
;                 const float v1 = bias[2 * e + 1] + wgt[0][2 * e + 1] * x3[2 * e + 1] + wgt[1][2 * e + 1] * x2[2 * e + 1] + wgt[2][2 * e + 1] * x1[2 * e + 1] + wgt[3][2 * e + 1] * x0[2 * e + 1];
;                 o[e] = pk2(silu_f(v0) * sc, silu_f(v1) * sc); }
;             *(u32x4*)(dst0 + (size_t)(R0 + i) * 512) = o;
; #pragma unroll
;             for (int e = 0; e < 8; ++e) { x3[e] = x2[e]; x2[e] = x1[e]; x1[e] = x0[e]; }
;         }
; __global__ void __launch_bounds__(512, 2) mega(Args a) {
;     ...
;             __syncthreads();
	v_mov_b32_e32 v84, v248
	v_mov_b32_e32 v85, v249
	v_mov_b32_e32 v86, v250
	v_mov_b32_e32 v87, v251
	global_load_dwordx4 v[248:251], v[252:253], off
	v_lshl_add_u64 v[252:253], v[252:253], 0, s[98:99]
	v_lshlrev_b32_e32 v77, 16, v84
	v_and_b32_e32 v75, 0xffff0000, v84
	v_lshlrev_b32_e32 v73, 16, v85
	v_and_b32_e32 v71, 0xffff0000, v85
	v_lshlrev_b32_e32 v69, 16, v86
	v_and_b32_e32 v67, 0xffff0000, v86
	v_lshlrev_b32_e32 v65, 16, v87
	v_and_b32_e32 v63, 0xffff0000, v87
	v_pk_mul_f32 v[78:79], v[26:27], v[76:77]
	v_pk_mul_f32 v[80:81], v[0:1], v[74:75]
	v_pk_mul_f32 v[82:83], v[32:33], v[72:73]
	v_pk_mul_f32 v[84:85], v[2:3], v[70:71]
	v_pk_mul_f32 v[86:87], v[34:35], v[68:69]
	v_pk_mul_f32 v[88:89], v[4:5], v[66:67]
	v_pk_mul_f32 v[90:91], v[50:51], v[64:65]
	v_pk_mul_f32 v[92:93], v[6:7], v[62:63]
	v_mov_b32_e32 v62, v77
	v_mov_b32_e32 v64, v75
	v_mov_b32_e32 v66, v73
	v_mov_b32_e32 v68, v71
	v_mov_b32_e32 v70, v69
	v_mov_b32_e32 v72, v67
	v_mov_b32_e32 v74, v65
	v_mov_b32_e32 v76, v63
	v_add_f32_e32 v63, v78, v110
	v_add_f32_e32 v65, v80, v111
	v_add_f32_e32 v67, v82, v113
	v_add_f32_e32 v69, v84, v114
	v_add_f32_e32 v71, v86, v115
	v_add_f32_e32 v73, v88, v116
	v_add_f32_e32 v75, v90, v117
	v_add_f32_e32 v77, v92, v118
	v_add_f32_e32 v63, v63, v79
	v_add_f32_e32 v65, v65, v81
	v_add_f32_e32 v67, v67, v83
	v_add_f32_e32 v69, v69, v85
	v_add_f32_e32 v71, v71, v87
	v_add_f32_e32 v73, v73, v89
	v_add_f32_e32 v75, v75, v91
	v_add_f32_e32 v77, v77, v93
	v_mul_f32_e32 v78, 0xbfb8aa3b, v63
	v_mul_f32_e32 v79, 0xbfb8aa3b, v65
	v_mul_f32_e32 v80, 0xbfb8aa3b, v67
	v_mul_f32_e32 v81, 0xbfb8aa3b, v69
	v_mul_f32_e32 v82, 0xbfb8aa3b, v71
	v_mul_f32_e32 v83, 0xbfb8aa3b, v73
	v_mul_f32_e32 v84, 0xbfb8aa3b, v75
	v_mul_f32_e32 v85, 0xbfb8aa3b, v77
	v_exp_f32_e32 v78, v78
	v_exp_f32_e32 v79, v79
	v_exp_f32_e32 v80, v80
	v_exp_f32_e32 v81, v81
	v_exp_f32_e32 v82, v82
	v_exp_f32_e32 v83, v83
	v_exp_f32_e32 v84, v84
	v_exp_f32_e32 v85, v85
	v_add_f32_e32 v78, 1.0, v78
	v_add_f32_e32 v79, 1.0, v79
	v_add_f32_e32 v80, 1.0, v80
	v_add_f32_e32 v81, 1.0, v81
	v_add_f32_e32 v82, 1.0, v82
	v_add_f32_e32 v83, 1.0, v83
	v_add_f32_e32 v84, 1.0, v84
	v_add_f32_e32 v85, 1.0, v85
	v_rcp_f32_e32 v78, v78
	v_rcp_f32_e32 v79, v79
	v_rcp_f32_e32 v80, v80
	v_rcp_f32_e32 v81, v81
	v_rcp_f32_e32 v82, v82
	v_rcp_f32_e32 v83, v83
	v_rcp_f32_e32 v84, v84
	v_rcp_f32_e32 v85, v85
	v_mul_f32_e32 v63, v63, v78
	v_mul_f32_e32 v65, v65, v79
	v_mul_f32_e32 v67, v67, v80
	v_mul_f32_e32 v69, v69, v81
	v_mul_f32_e32 v71, v71, v82
	v_mul_f32_e32 v73, v73, v83
	v_mul_f32_e32 v75, v75, v84
	v_mul_f32_e32 v77, v77, v85
	v_mul_f32_e32 v63, v112, v63
	v_mul_f32_e32 v65, v112, v65
	v_mul_f32_e32 v67, v112, v67
	v_mul_f32_e32 v69, v112, v69
	v_mul_f32_e32 v71, v112, v71
	v_mul_f32_e32 v73, v112, v73
	v_mul_f32_e32 v75, v112, v75
	v_mul_f32_e32 v77, v112, v77
	v_cvt_pk_bf16_f32 v78, v63, v65
	v_cvt_pk_bf16_f32 v79, v67, v69
	v_cvt_pk_bf16_f32 v80, v71, v73
	v_cvt_pk_bf16_f32 v81, v75, v77
	global_store_dwordx4 v[60:61], v[78:81], off offset:3072
	s_cbranch_scc1 .LBB0_454
	v_mov_b32_e32 v138, v189
	s_waitcnt lgkmcnt(0)
	s_barrier
; #define LAS __attribute__((address_space(3)))
; __device__ __forceinline__ int tid_here() { int t = threadIdx.x; asm volatile("" : "+v"(t)); return t; }
; __device__ __forceinline__ void mlstm_pass1(const bf16_t* PR, const bf16_t* QC, const bf16_t* KC, const float* Gt, const float* gain, bf16_t* Y, LAS unsigned char* lds, ...
;     const int tid = tid_here(), lane = tid & 63, w = __builtin_amdgcn_readfirstlane(tid >> 6);
;     const int r = lane & 31, h = lane >> 5, li = lane & 15, gg = (lane >> 4) & 1;
;     LAS float* cs_t = (LAS float*)(lds + ML_TAB); LAS float* den_t = cs_t + 64; LAS float* ssq_t = cs_t + 128;
;     for (int st = st_first; st < 256; st += st_stride) {
;         const int b = st >> 4, hm = (st >> 2) & 3, seg = st & 3;
;         __syncthreads();
;         for (int i = tid; i < 64 * OROW / 4; i += 512) { ((LAS unsigned*)(lds + ML_ONE_T))[i] = ((i % (OROW / 4)) == 0) ? 0x00003f80u : 0u; ((LAS unsigned*)(lds + ML_ONE_W))[i] = 0u; }
;         __syncthreads();
;         f32x16 C[4];
; #pragma unroll
;         for (int i = 0; i < 4; ++i)
; #pragma unroll
;             for (int e = 0; e < 16; ++e) C[i][e] = 0.f;
;         const LAS unsigned char* vtb = (w < 4) ? (lds + ML_VT + 64 * w) : (lds + ML_ONE_T);
;         const LAS unsigned char* vwb = (w < 4) ? (lds + ML_VW + 64 * w) : (lds + ML_ONE_W);
;         const int vstr = (w < 4) ? KROW : OROW;
;         float Bseg = 0.f;
;         const int frow = tid >> 4, fch = tid & 15;
;         const size_t rs0 = (size_t)b * SEQL + 64 * (8 * seg);
;         const bf16_t* pK = KC + (rs0 + frow) * 512 + hm * 128 + 8 * fch; const bf16_t* pQ = QC + (rs0 + frow) * 512 + hm * 128 + 8 * fch;
;         const bf16_t* pV = PR + (rs0 + frow) * PW + PC_VM + hm * 128 + 8 * fch; const float* pG = Gt + (rs0 + lane) * 8 + hm;
	s_movk_i32 s1, 0x500
	v_readfirstlane_b32 s0, v138
	s_ashr_i32 s93, s0, 6
	s_cmp_gt_i32 s93, 3
	v_cmp_gt_i32_e64 s[2:3], s1, v138
	s_cselect_b64 s[88:89], -1, 0
	s_and_b32 s1, s0, 0xffffffc0
	v_writelane_b32 v234, s2, 5
	s_add_i32 s1, s1, 0
	v_and_b32_e32 v140, 63, v138
	v_writelane_b32 v234, s3, 6
	s_add_i32 s2, s1, 0x4400
	s_add_i32 s1, s1, 0x8800
	s_cmp_lt_i32 s93, 4
	v_readlane_b32 s68, v234, 2
	v_readlane_b32 s3, v234, 3
	s_cselect_b32 s2, s2, s68
	s_cselect_b32 s87, s33, 0x50
	s_cselect_b32 s3, s1, s3
	s_lshl_b32 s1, s93, 13
	s_add_i32 s1, s1, 0
	s_cmp_lt_u32 s0, 64
	s_cselect_b64 s[96:97], -1, 0
	s_cmp_lt_i32 s93, 5
	v_bfe_u32 v1, v138, 5, 1
	s_cselect_b64 s[80:81], -1, 0
	s_lshl_b32 s72, s87, 3
	s_lshl_b32 s73, s87, 4
	s_lshl_b32 s5, s87, 5
	s_add_i32 s1, s1, 0x10000
	v_lshlrev_b32_e32 v4, 2, v140
	s_movk_i32 s0, 0x50
	v_lshlrev_b32_e32 v8, 2, v1
	v_bfe_u32 v9, v138, 2, 2
	s_cmp_eq_u32 s93, 4
	v_mad_u32_u24 v164, v140, s0, 0
	v_or_b32_e32 v10, v8, v9
	v_mov_b32_e32 v11, s2
	v_add_u32_e32 v168, s1, v4
	s_cselect_b64 s[0:1], -1, 0
	v_cmp_gt_u32_e32 vcc, 32, v140
	v_lshlrev_b32_e32 v6, 3, v1
	v_mad_u32_u24 v10, v10, s87, v11
	v_lshlrev_b32_e32 v11, 1, v138
	v_lshlrev_b32_e32 v12, 3, v138
	s_and_b64 s[82:83], s[0:1], vcc
	s_lshl_b32 s0, s93, 5
	v_and_b32_e32 v11, 32, v11
	v_and_b32_e32 v12, 24, v12
	v_lshlrev_b32_e32 v136, 4, v1
	v_or_b32_e32 v1, v6, v9
	s_ashr_i32 s1, s0, 31
	v_ashrrev_i32_e32 v144, 4, v138
	v_add3_u32 v166, v10, v11, v12
	v_mul_u32_u24_e32 v9, s87, v1
	v_or_b32_e32 v10, v11, v12
	s_lshl_b64 s[0:1], s[0:1], 2
	v_readlane_b32 s2, v235, 50
	v_add3_u32 v169, s3, v9, v10
	s_add_u32 s0, s2, s0
	v_readlane_b32 s2, v235, 51
	v_add_u32_e32 v9, 32, v144
	v_and_b32_e32 v142, 31, v138
	s_addc_u32 s1, s2, s1
	v_and_or_b32 v9, v9, 63, v143
	v_lshl_add_u64 v[146:147], s[0:1], 0, v[136:137]
	v_readlane_b32 s0, v235, 56
	v_lshlrev_b32_e32 v172, 2, v9
	v_cmp_le_u32_e64 s[8:9], v8, v142
	v_cmp_lt_u32_e64 s[10:11], v8, v142
	v_or_b32_e32 v9, 2, v8
	v_or_b32_e32 v11, 3, v8
	v_or_b32_e32 v12, 8, v8
	v_or_b32_e32 v13, 9, v8
	v_or_b32_e32 v14, 10, v8
	v_or_b32_e32 v15, 11, v8
	v_or_b32_e32 v16, 16, v8
	v_or_b32_e32 v17, 17, v8
	v_or_b32_e32 v18, 18, v8
	v_or_b32_e32 v19, 19, v8
	v_or_b32_e32 v20, 24, v8
	v_or_b32_e32 v21, 25, v8
	v_or_b32_e32 v22, 26, v8
	v_or_b32_e32 v23, 27, v8
	v_cmp_gt_u32_e64 s[42:43], v8, v142
	v_max_i32_e32 v8, 0x300, v138
	v_add_u32_e32 v167, 0, v136
	v_lshlrev_b32_e32 v136, 8, v140
	v_readlane_b32 s1, v235, 57
	v_sub_u32_e32 v8, v8, v138
	v_add_u32_e32 v8, 0x1ff, v8
	v_lshl_add_u64 v[148:149], s[0:1], 0, v[136:137]
	v_cmp_eq_u32_e64 s[0:1], 0, v138
	v_readlane_b32 s4, v234, 4
	v_cmp_le_u32_e64 s[12:13], v9, v142
	v_writelane_b32 v234, s0, 7
	v_cmp_gt_u32_e64 s[44:45], v9, v142
	v_lshrrev_b32_e32 v9, 9, v8
	v_writelane_b32 v234, s1, 8
	v_add_u32_e32 v9, 1, v9
	v_cmp_lt_u32_e64 s[0:1], s74, v8
	v_and_b32_e32 v2, 15, v138
	v_and_b32_e32 v173, 0xfffffe, v9
	v_writelane_b32 v234, s0, 9
	v_lshlrev_b32_e32 v0, 3, v2
	v_lshlrev_b32_e32 v2, 4, v2
	v_add_u32_e32 v170, 0, v4
	v_and_or_b32 v4, v144, 63, v143
	v_writelane_b32 v234, s1, 10
	v_cmp_ne_u32_e64 s[0:1], v9, v173
	v_add_u32_e32 v3, 0, v2
	v_add_u32_e32 v2, s4, v2
	v_mul_i32_i24_e32 v5, 0xffffffb4, v140
	v_mad_u32_u24 v7, v142, s33, 0
	v_mad_u32_u24 v1, v1, s33, 0
	v_lshlrev_b32_e32 v171, 2, v4
	v_mul_lo_u32 v4, v144, s33
	v_lshlrev_b32_e32 v175, 2, v138
	v_writelane_b32 v234, s0, 11
	v_ashrrev_i32_e32 v145, 31, v144
	v_add_u32_e32 v165, s4, v6
	s_mul_i32 s4, s87, 24
	s_mul_i32 s6, s87, 40
	s_mul_i32 s7, s87, 48
	s_mul_i32 s92, s87, 56
	v_cmp_le_u32_e64 s[14:15], v11, v142
	v_cmp_le_u32_e64 s[16:17], v12, v142
	v_cmp_le_u32_e64 s[18:19], v13, v142
	v_cmp_le_u32_e64 s[20:21], v14, v142
	v_cmp_le_u32_e64 s[22:23], v15, v142
	v_cmp_le_u32_e64 s[24:25], v16, v142
	v_cmp_le_u32_e64 s[26:27], v17, v142
	v_cmp_le_u32_e64 s[28:29], v18, v142
	v_cmp_le_u32_e64 s[30:31], v19, v142
	v_cmp_le_u32_e64 s[34:35], v20, v142
	v_cmp_le_u32_e64 s[36:37], v21, v142
	v_cmp_le_u32_e64 s[38:39], v22, v142
	v_cmp_le_u32_e64 s[40:41], v23, v142
	v_cmp_gt_u32_e64 s[46:47], v11, v142
	v_cmp_gt_u32_e64 s[48:49], v12, v142
	v_cmp_gt_u32_e64 s[50:51], v13, v142
	v_cmp_gt_u32_e64 s[52:53], v14, v142
	v_cmp_gt_u32_e64 s[54:55], v15, v142
	v_cmp_gt_u32_e64 s[56:57], v16, v142
	v_cmp_gt_u32_e64 s[58:59], v17, v142
	v_cmp_gt_u32_e64 s[60:61], v18, v142
	v_cmp_gt_u32_e64 s[62:63], v19, v142
	v_cmp_gt_u32_e64 s[64:65], v20, v142
	v_cmp_gt_u32_e64 s[66:67], v21, v142
	s_lshl_b32 s84, s87, 2
	s_mul_i32 s85, s87, 20
	s_mul_i32 s86, s87, 36
	s_mul_i32 s87, s87, 52
	v_or_b32_e32 v150, 32, v142
	v_lshl_add_u32 v174, v173, 9, v138
	v_add_u32_e32 v139, 0x200, v138
	v_add_u32_e32 v176, s68, v175
	v_lshlrev_b32_e32 v136, 1, v0
	v_add_u32_e32 v177, v3, v4
	v_add_u32_e32 v178, v2, v4
	v_add_u32_e32 v179, v164, v5
	v_add_u32_e32 v180, v7, v6
	v_add_u32_e32 v181, v1, v10
	v_cmp_gt_u32_e64 s[68:69], v22, v142
	v_cmp_gt_u32_e64 s[70:71], v23, v142
	v_writelane_b32 v234, s1, 12
	s_mov_b32 s90, s75
	v_writelane_b32 v234, s75, 13
	s_branch .LBB0_457

; #define LAS __attribute__((address_space(3)))
; __device__ __forceinline__ void mlstm_pass1(const bf16_t* PR, const bf16_t* QC, const bf16_t* KC, const float* Gt, const float* gain, bf16_t* Y, LAS unsigned char* lds, ...
;     ...
;     LAS float* cs_t = (LAS float*)(lds + ML_TAB); LAS float* den_t = cs_t + 64; LAS float* ssq_t = cs_t + 128;
;     for (int st = st_first; st < 256; st += st_stride) {
;         const int b = st >> 4, hm = (st >> 2) & 3, seg = st & 3;
;         __syncthreads();
;         for (int i = tid; i < 64 * OROW / 4; i += 512) { ((LAS unsigned*)(lds + ML_ONE_T))[i] = ((i % (OROW / 4)) == 0) ? 0x00003f80u : 0u; ((LAS unsigned*)(lds + ML_ONE_W))[i] = 0u; }
;         __syncthreads();
;         f32x16 C[4];
; #pragma unroll
;         for (int i = 0; i < 4; ++i)
; #pragma unroll
;             for (int e = 0; e < 16; ++e) C[i][e] = 0.f;
;         const LAS unsigned char* vtb = (w < 4) ? (lds + ML_VT + 64 * w) : (lds + ML_ONE_T);
;         const LAS unsigned char* vwb = (w < 4) ? (lds + ML_VW + 64 * w) : (lds + ML_ONE_W);
;         const int vstr = (w < 4) ? KROW : OROW;
;         float Bseg = 0.f;
;         const int frow = tid >> 4, fch = tid & 15;
;         const size_t rs0 = (size_t)b * SEQL + 64 * (8 * seg);
;         const bf16_t* pK = KC + (rs0 + frow) * 512 + hm * 128 + 8 * fch; const bf16_t* pQ = QC + (rs0 + frow) * 512 + hm * 128 + 8 * fch;
;         const bf16_t* pV = PR + (rs0 + frow) * PW + PC_VM + hm * 128 + 8 * fch; const float* pG = Gt + (rs0 + lane) * 8 + hm;
;         u32x4 fK[2], fV[2], fQ[2]; float f_ip, f_fp;
; #pragma unroll
;         for (int p = 0; p < 2; ++p) { fK[p] = *(const u32x4*)(pK + (size_t)32 * p * 512); fQ[p] = *(const u32x4*)(pQ + (size_t)32 * p * 512); fV[p] = *(const u32x4*)(pV + (size_t)32 * p * PW); }
;         f_ip = pG[0]; f_fp = pG[4];
.LBB0_467:
	s_or_b64 exec, exec, s[0:1]
	s_ashr_i32 s0, s90, 4
	s_ashr_i32 s1, s0, 31
	s_lshl_b64 s[2:3], s[0:1], 11
	s_lshl_b32 s0, s90, 9
	s_and_b32 s0, s0, 0x600
	s_or_b32 s2, s2, s0
	v_lshl_add_u64 v[0:1], s[2:3], 0, v[144:145]
	v_readlane_b32 s0, v235, 46
	v_lshlrev_b64 v[2:3], 10, v[0:1]
	v_readlane_b32 s1, v235, 47
	s_bfe_u32 s74, s90, 0x20002
	s_lshl_b32 s76, s74, 8
	v_lshl_add_u64 v[4:5], s[0:1], 0, v[2:3]
	v_readlane_b32 s0, v234, 0
	v_readlane_b32 s1, v234, 1
	s_mov_b32 s77, s1
	v_readlane_b32 s0, v235, 44
	v_readlane_b32 s1, v235, 45
	s_movk_i32 s75, 0x1c00
	v_lshl_add_u64 v[4:5], v[4:5], 0, s[76:77]
	v_lshl_add_u64 v[2:3], s[0:1], 0, v[2:3]
	v_readlane_b32 s0, v235, 42
	v_lshl_add_u64 v[2:3], v[2:3], 0, s[76:77]
	v_readlane_b32 s1, v235, 43
	v_lshl_add_u64 v[154:155], v[2:3], 0, v[136:137]
	v_lshl_add_u64 v[152:153], v[4:5], 0, v[136:137]
	v_mov_b64_e32 v[2:3], s[0:1]
	v_mad_u64_u32 v[2:3], s[0:1], v0, s75, v[2:3]
	v_mad_i32_i24 v3, v1, s75, v3
	v_lshl_add_u64 v[0:1], v[2:3], 0, s[76:77]
	v_lshl_add_u64 v[0:1], v[0:1], 0, v[136:137]
	s_movk_i32 s0, 0x1000
	v_add_co_u32_e32 v4, vcc, s0, v0
	s_mov_b32 s0, 0x8000
	s_nop 0
	v_addc_co_u32_e32 v5, vcc, 0, v1, vcc
	v_add_co_u32_e32 v6, vcc, s0, v152
	s_waitcnt lgkmcnt(0)
	s_nop 0
	v_addc_co_u32_e32 v7, vcc, 0, v153, vcc
	s_barrier
	s_waitcnt vmcnt(0)
	global_load_dwordx4 v[112:115], v[152:153], off
	global_load_dwordx4 v[116:119], v[154:155], off
	global_load_dwordx4 v[120:123], v[4:5], off offset:1024
	global_load_dwordx4 v[124:127], v[6:7], off
	v_add_co_u32_e32 v4, vcc, s0, v154
	s_mov_b32 s0, 0x39000
	s_nop 0
	v_addc_co_u32_e32 v5, vcc, 0, v155, vcc
	v_mov_b32_e32 v3, s3
	v_or_b32_e32 v2, s2, v140
	v_add_co_u32_e32 v6, vcc, s0, v0
	v_readlane_b32 s0, v235, 48
	v_lshlrev_b64 v[2:3], 5, v[2:3]
	v_readlane_b32 s1, v235, 49
	s_lshl_b32 s76, s74, 2
	v_addc_co_u32_e32 v7, vcc, 0, v1, vcc
	v_lshl_add_u64 v[2:3], s[0:1], 0, v[2:3]
	v_lshl_add_u64 v[156:157], v[2:3], 0, s[76:77]
	global_load_dwordx4 v[128:131], v[4:5], off
	global_load_dwordx4 v[132:135], v[6:7], off offset:1024
	global_load_dword v183, v[156:157], off
	global_load_dword v184, v[156:157], off offset:16
	s_mov_b64 s[0:1], 0x1400
	v_lshl_add_u64 v[158:159], v[0:1], 0, s[0:1]
	v_readlane_b32 s0, v235, 54
	s_add_u32 vcc_lo, s0, s76
	v_readlane_b32 s0, v235, 55
	s_addc_u32 vcc_hi, s0, 0
	v_writelane_b32 v234, vcc_lo, 14
	v_readlane_b32 s0, v235, 52
	v_mov_b32_e32 v32, v137
	v_writelane_b32 v234, vcc_hi, 15
	s_add_u32 vcc_lo, s0, s76
	v_readlane_b32 s0, v235, 53
	s_addc_u32 vcc_hi, s0, 0
	v_writelane_b32 v234, vcc_lo, 16
	v_mov_b32_e32 v33, v137
	v_mov_b32_e32 v46, v137
	v_mov_b32_e32 v47, v137
	v_writelane_b32 v234, vcc_hi, 17
	s_lshl_b32 s76, s74, 9
	s_mov_b32 s1, s77
	v_mov_b32_e32 v34, v137
	v_mov_b32_e32 v35, v137
	v_mov_b32_e32 v36, v137
	v_mov_b32_e32 v37, v137
	v_mov_b32_e32 v38, v137
	v_mov_b32_e32 v39, v137
	v_mov_b32_e32 v40, v137
	v_mov_b32_e32 v41, v137
	v_mov_b32_e32 v42, v137
	v_mov_b32_e32 v43, v137
	v_mov_b32_e32 v44, v137
	v_mov_b32_e32 v45, v137
	v_mov_b64_e32 v[62:63], v[46:47]
	v_mov_b64_e32 v[16:17], v[32:33]
	v_mov_b64_e32 v[0:1], v[32:33]
	s_movk_i32 s79, 0x1c00
	s_mov_b32 s91, 0
	v_writelane_b32 v234, s0, 0
	v_lshl_add_u64 v[160:161], v[146:147], 0, s[76:77]
	v_mov_b32_e32 v182, 0
	v_mov_b64_e32 v[60:61], v[44:45]
	v_mov_b64_e32 v[58:59], v[42:43]
	v_mov_b64_e32 v[56:57], v[40:41]
	v_mov_b64_e32 v[54:55], v[38:39]
	v_mov_b64_e32 v[52:53], v[36:37]
	v_mov_b64_e32 v[50:51], v[34:35]
	v_mov_b64_e32 v[48:49], v[32:33]
	v_mov_b64_e32 v[18:19], v[34:35]
	v_mov_b64_e32 v[20:21], v[36:37]
	v_mov_b64_e32 v[22:23], v[38:39]
	v_mov_b64_e32 v[24:25], v[40:41]
	v_mov_b64_e32 v[26:27], v[42:43]
	v_mov_b64_e32 v[28:29], v[44:45]
	v_mov_b64_e32 v[30:31], v[46:47]
	v_mov_b64_e32 v[2:3], v[34:35]
	v_mov_b64_e32 v[4:5], v[36:37]
	v_mov_b64_e32 v[6:7], v[38:39]
	v_mov_b64_e32 v[8:9], v[40:41]
	v_mov_b64_e32 v[10:11], v[42:43]
	v_mov_b64_e32 v[12:13], v[44:45]
	v_mov_b64_e32 v[14:15], v[46:47]
	v_writelane_b32 v234, s1, 1
	s_waitcnt vmcnt(0)
	s_branch .LBB0_469

; #define LAS __attribute__((address_space(3)))
; __device__ __forceinline__ unsigned pk2(float lo, float hi) { return pg8::cvt_pk_bf16(lo, hi); }
; __device__ __forceinline__ unsigned short f2bf1(float f) { return (unsigned short)(pk2(f, 0.f) & 0xffffu); }
; __device__ __forceinline__ void mlstm_pass1(const bf16_t* PR, const bf16_t* QC, const bf16_t* KC, const float* Gt, const float* gain, bf16_t* Y, LAS unsigned char* lds, ...
;     ...
;         for (int cc = 0; cc < 8; ++cc) {
;             const size_t r0 = rs0 + 64 * cc;
;             const float ip = f_ip, fp = f_fp;
;             const float lf = -__logf(1.f + __expf(-fp));
;             const float bsum = wave_incl_scan(lf);
;             const float bL = __int_as_float(__builtin_amdgcn_readlane(__float_as_int(bsum), 63)), csv = ip - bsum, wgt = __expf(bL + csv), decay = __expf(bL);
; #pragma unroll
;             for (int p = 0; p < 2; ++p) { const int row = frow + 32 * p;
;                 const float wr_ = __shfl(wgt, row);
;                 u32x4 vw;
; #pragma unroll
;                 for (int e = 0; e < 4; ++e) vw[e] = pk2(__uint_as_float(fV[p][e] << 16) * wr_, __uint_as_float(fV[p][e] & 0xffff0000u) * wr_);
;                 *(LAS u32x4*)(lds + ML_KT + row * KROW + 16 * fch) = fK[p]; *(LAS u32x4*)(lds + ML_VT + row * KROW + 16 * fch) = fV[p];
;                 *(LAS u32x4*)(lds + ML_VW + row * KROW + 16 * fch) = vw; *(LAS u32x4*)(lds + ML_QT + row * KROW + 16 * fch) = fQ[p]; }
;             if (w == 0) { cs_t[lane] = csv; *(LAS unsigned short*)(lds + ML_ONE_W + lane * OROW) = f2bf1(wgt); }
.LBB0_469:
	s_waitcnt lgkmcnt(0)
	v_mul_f32_e32 v64, 0xbfb8aa3b, v184
	v_exp_f32_e32 v64, v64
	s_mov_b32 s0, 0x800000
	v_mov_b32_e32 v66, 0
	v_and_b32_e32 v70, 0xffff0000, v121
	v_add_f32_e32 v64, 1.0, v64
	v_cmp_gt_f32_e32 vcc, s0, v64
	s_mov_b32 s0, 0x3f317217
	v_and_b32_e32 v71, 0xffff0000, v123
	v_cndmask_b32_e64 v65, 0, 32, vcc
	v_ldexp_f32 v64, v64, v65
	v_log_f32_e32 v64, v64
	v_cndmask_b32_e32 v67, 0, v162, vcc
	v_mov_b32_e32 v65, 0
	v_mul_f32_e32 v68, 0x3f317217, v64
	v_fma_f32 v68, v64, s0, -v68
	v_fmac_f32_e32 v68, 0x3377d1cf, v64
	s_mov_b32 s0, 0x7f800000
	v_fmac_f32_e32 v68, 0x3f317217, v64
	v_cmp_lt_f32_e64 vcc, |v64|, s0
	s_nop 1
	v_cndmask_b32_e32 v64, v64, v68, vcc
	v_sub_f32_e32 v64, v64, v67
	v_xor_b32_e32 v67, 0x80000000, v64
	v_lshlrev_b32_e32 v68, 16, v121
	s_andn2_b64 vcc, exec, s[96:97]
	v_sub_f32_dpp v64, v67, v64 row_shr:1 row_mask:0xf bank_mask:0xf bound_ctrl:1
	v_and_b32_e32 v67, 0xffff0000, v120
	s_nop 0
	v_add_f32_dpp v64, v64, v64 row_shr:2 row_mask:0xf bank_mask:0xf bound_ctrl:1
	s_nop 1
	v_add_f32_dpp v64, v64, v64 row_shr:4 row_mask:0xf bank_mask:0xf bound_ctrl:1
	s_nop 1
	v_add_f32_dpp v64, v64, v64 row_shr:8 row_mask:0xf bank_mask:0xf bound_ctrl:1
	s_nop 1
	v_mov_b32_dpp v65, v64 row_bcast:15 row_mask:0xa bank_mask:0xf bound_ctrl:1
	v_add_f32_e32 v64, v64, v65
	s_nop 1
	v_mov_b32_dpp v66, v64 row_bcast:31 row_mask:0xc bank_mask:0xf bound_ctrl:1
	v_add_f32_e32 v185, v64, v66
	v_sub_f32_e32 v64, v183, v185
	v_readlane_b32 s74, v185, 63
	v_lshlrev_b32_e32 v66, 16, v120
	s_nop 0
	v_add_f32_e32 v65, s74, v64
	v_mul_f32_e32 v65, 0x3fb8aa3b, v65
	v_exp_f32_e32 v65, v65
	ds_bpermute_b32 v69, v171, v65
	s_waitcnt lgkmcnt(0)
	v_mul_f32_e32 v66, v66, v69
	v_mul_f32_e32 v67, v67, v69
	v_mul_f32_e32 v68, v68, v69
	v_mul_f32_e32 v70, v70, v69
	v_cvt_pk_bf16_f32 v66, v66, v67
	v_cvt_pk_bf16_f32 v67, v68, v70
	v_lshlrev_b32_e32 v68, 16, v122
	v_and_b32_e32 v70, 0xffff0000, v122
	v_mul_f32_e32 v68, v68, v69
	v_mul_f32_e32 v70, v70, v69
	v_cvt_pk_bf16_f32 v68, v68, v70
	v_lshlrev_b32_e32 v70, 16, v123
	v_mul_f32_e32 v70, v70, v69
	v_mul_f32_e32 v69, v71, v69
	v_cvt_pk_bf16_f32 v69, v70, v69
	ds_bpermute_b32 v70, v172, v65
	ds_write_b128 v177, v[112:115]
	ds_write_b128 v177, v[120:123] offset:17408
	ds_write_b128 v177, v[66:69] offset:34816
	ds_write_b128 v178, v[116:119]
	v_lshlrev_b32_e32 v66, 16, v132
	v_and_b32_e32 v67, 0xffff0000, v132
	s_waitcnt lgkmcnt(4)
	v_mul_f32_e32 v66, v66, v70
	v_mul_f32_e32 v67, v67, v70
	v_cvt_pk_bf16_f32 v66, v66, v67
	v_lshlrev_b32_e32 v67, 16, v133
	v_and_b32_e32 v68, 0xffff0000, v133
	v_mul_f32_e32 v67, v67, v70
	v_mul_f32_e32 v68, v68, v70
	v_cvt_pk_bf16_f32 v67, v67, v68
	v_lshlrev_b32_e32 v68, 16, v134
	v_and_b32_e32 v69, 0xffff0000, v134
	v_mul_f32_e32 v68, v68, v70
	v_mul_f32_e32 v69, v69, v70
	v_cvt_pk_bf16_f32 v68, v68, v69
	v_lshlrev_b32_e32 v69, 16, v135
	v_mul_f32_e32 v69, v69, v70
	v_and_b32_e32 v71, 0xffff0000, v135
	v_mul_f32_e32 v70, v71, v70
	v_cvt_pk_bf16_f32 v69, v69, v70
	ds_write_b128 v177, v[124:127] offset:8704
	ds_write_b128 v177, v[132:135] offset:26112
	ds_write_b128 v177, v[66:69] offset:43520
	ds_write_b128 v178, v[128:131] offset:8704
	s_cbranch_vccnz .LBB0_471
	ds_write_b32 v179, v64 offset:62464
	v_cvt_pk_bf16_f32 v64, v65, v137
	ds_write_b16 v164, v64 offset:57344

; #define LAS __attribute__((address_space(3)))
; __device__ __forceinline__ void mlstm_pass1(const bf16_t* PR, const bf16_t* QC, const bf16_t* KC, const float* Gt, const float* gain, bf16_t* Y, LAS unsigned char* lds, ...
;     ...
;             __syncthreads();
;             f32x16 res[2];
;             if (w < 4) { const LAS float* pk_ = (const LAS float*)(lds + ML_PARK + w * 8192) + lane;
; #pragma unroll
;                 for (int tt = 0; tt < 2; ++tt)
; #pragma unroll
;                     for (int e = 0; e < 16; ++e) res[tt][e] = pk_[tt * 1024 + e * 64]; }
;             {
;                 if (w < 4) {
; #pragma unroll
;                     for (int tt = 0; tt < 2; ++tt) { float* np = num_ptr(NB, r0 + 32 * tt + r, hm) + 32 * w + 4 * h;
; #pragma unroll
;                         for (int g4 = 0; g4 < 4; ++g4) *(f32x4*)(np + 8 * g4) = (f32x4){res[tt][4 * g4], res[tt][4 * g4 + 1], res[tt][4 * g4 + 2], res[tt][4 * g4 + 3]}; }
;                 } else if (w == 4) { DEN[(r0 + lane) * 4 + hm] = den_t[lane]; }
;                 else if (w == 5) { BC[(r0 + lane) * 4 + hm] = Bseg + bsum; }
;             }
;             Bseg += bL;
.LBB0_481:
	s_lshl_b32 s0, s91, 6
	s_or_b32 s75, s2, s0
	s_mov_b64 s[0:1], -1
	s_and_b64 vcc, exec, s[88:89]
	s_waitcnt vmcnt(0)
	s_barrier
	s_cbranch_vccnz .LBB0_483
	s_and_b64 vcc, exec, s[0:1]
	s_cbranch_vccz .LBB0_468
	s_branch .LBB0_490

; #define LAS __attribute__((address_space(3)))
; #define LFENCE() asm volatile("" ::: "memory")
; template <int MODE> ...
;     const int r = lane & 31, h = lane >> 5, li = lane & 15, gg = (lane >> 4) & 1;
;     const size_t seqrow0 = (size_t)b * SEQL + res;
;     const int q0 = 32 * qt;
;     const size_t rstride = (size_t)dil * PW;
;     bf16x8 qf[4];
;     { const bf16_t* qp = PR + (seqrow0 + (size_t)(q0 + r) * dil) * PW + PC_QA + head * 64 + 8 * h;
; #pragma unroll
;       for (int s = 0; s < 4; ++s) qf[s] = *(const bf16x8*)(qp + 16 * s); }
;     f32x16 o[2];
; #pragma unroll
;     for (int dt = 0; dt < 2; ++dt)
; #pragma unroll
;         for (int i = 0; i < 16; ++i) o[dt][i] = 0.f;
;     float l = 0.f;
;     const float slope = exp2f(-(float)(head + 1)) * LOG2E * (float)dil;
;     const LAS unsigned char* trb = vl + (4 * h + (li >> 2)) * VROW + (16 * gg + 4 * (li & 3)) * 2;
;     const int first = (q0 >= 128) ? 0 : ((128 - q0) >> 5);
;     const size_t prow = (seqrow0 + (size_t)(q0 - 128 + 32 * first + (lane >> 3)) * dil) * PW + head * 64 + 8 * (lane & 7);
;     const bf16_t* kp = PR + prow + PC_KA; const bf16_t* vp = PR + prow + PC_VA;
;     LAS unsigned char* kl = vl + 4608;
;     const int stoff = (lane >> 3) * VROW + 16 * (lane & 7);
;     u32x4 kn[4], vn[4];
; #pragma unroll
;     for (int i = 0; i < 4; ++i) { kn[i] = *(const u32x4*)(kp + (size_t)(8 * i) * rstride); vn[i] = *(const u32x4*)(vp + (size_t)(8 * i) * rstride); }
;     const int rr = r - 4 * h;
; #pragma unroll 1
;     for (int kt = first; kt < 5; ++kt) {
; #pragma unroll
;         for (int i = 0; i < 4; ++i) { *(LAS u32x4*)(kl + stoff + 8 * i * VROW) = kn[i]; *(LAS u32x4*)(vl + stoff + 8 * i * VROW) = vn[i]; }
;         LFENCE();
;         if (kt < 4) {
;             kp += 32 * rstride; vp += 32 * rstride;
; #pragma unroll
;             for (int i = 0; i < 4; ++i) { kn[i] = *(const u32x4*)(kp + (size_t)(8 * i) * rstride); vn[i] = *(const u32x4*)(vp + (size_t)(8 * i) * rstride); }
;         }
;         const float fb = slope * (float)(rr + 128 - 32 * kt);
;         f32x16 s;
; #pragma unroll
;         for (int i = 0; i < 16; ++i) s[i] = slope * (float)((i & 3) + 8 * (i >> 2)) - fb;
; __global__ void __launch_bounds__(512, 2) mega(Args a) {
;     ...
;             const int br = task >> 13, tk = task & 8191, bh = tk >> 6, wq = tk & 63;
.LBB0_498:
	s_bfe_u32 s72, s33, 0x60006
	s_and_b32 s75, s33, 7
	s_cmpk_lt_u32 s33, 0x2000
	s_cselect_b64 s[88:89], -1, 0
	s_and_b64 s[0:1], s[88:89], exec
	s_mov_b32 s76, 0x1c000
	s_cselect_b32 s94, s76, 0x70000
	s_mov_b32 s76, 0x38000
	s_cselect_b32 s95, s76, 0xe0000
	s_mov_b32 s76, 0x54000
	s_cselect_b32 s1, 15, 3
	s_cselect_b32 s96, s76, 0x150000
	s_mov_b32 s76, 0x1c0000
	s_cselect_b32 s0, 4, 2
	s_cselect_b32 s92, 4, 16
	s_cselect_b32 s93, 2, 4
	s_cselect_b32 s97, 0x70000, s76
	s_and_b32 s1, s1, s72
	s_lshr_b32 s0, s72, s0
	s_lshl_b32 s72, s33, 8
	s_lshl_b32 s98, s33, 2
	s_and_b32 s98, s98, 0x4000
	s_lshl_b32 s78, s1, 5
	s_and_b32 s72, s72, 0x3800
	s_or_b32 s72, s72, s98
	v_or_b32_e32 v0, s78, v111
	s_or_b32 s0, s0, s72
	v_lshlrev_b32_e32 v0, s93, v0
	v_add_u32_e32 v96, s0, v0
	v_mad_u64_u32 v[0:1], s[76:77], v96, s74, v[100:101]
	s_add_i32 s77, s75, 1
	s_nop 0
	v_cvt_f32_ubyte0_e32 v4, s77
	s_mov_b32 s77, 0x42fc0000
	s_lshl_b32 s76, s75, 6
	s_lshl_b32 s72, s75, 7
	v_cmp_lt_f32_e32 vcc, s77, v4
	s_and_b64 s[90:91], vcc, exec
	s_cselect_b32 s79, 0xffffffc0, 0
	s_sub_i32 s77, 0x80, s78
	s_ashr_i32 s77, s77, 5
	s_cmp_lt_u32 s1, 4
	s_cselect_b32 s77, s77, 0
	v_lshl_add_u64 v[0:1], v[0:1], 0, s[72:73]
	s_lshl_b32 s90, s77, 5
	v_lshl_add_u64 v[0:1], v[0:1], 0, v[102:103]
	s_add_i32 s1, s90, s78
	global_load_dwordx4 v[48:51], v[0:1], off
	global_load_dwordx4 v[52:55], v[0:1], off offset:32
	global_load_dwordx4 v[56:59], v[0:1], off offset:64
	global_load_dwordx4 v[60:63], v[0:1], off offset:96
	v_add_u32_e32 v0, s1, v126
	v_ashrrev_i32_e32 v1, 31, v0
	v_lshlrev_b64 v[0:1], s93, v[0:1]
	s_mov_b32 s1, s73
	v_lshl_add_u64 v[0:1], v[0:1], 0, s[0:1]
	v_mad_u64_u32 v[2:3], s[0:1], v0, s74, v[98:99]
	v_mad_i32_i24 v3, v1, s74, v3
	v_lshl_add_u64 v[0:1], v[2:3], 0, s[72:73]
	s_lshl_b32 s72, s96, 1
	v_lshl_add_u64 v[2:3], v[0:1], 0, s[72:73]
	s_lshl_b32 s72, s95, 1
	s_waitcnt vmcnt(0)
	global_load_dwordx4 v[84:87], v[2:3], off offset:2048
	global_load_dwordx4 v[72:75], v[2:3], off offset:1024
	v_lshl_add_u64 v[2:3], v[0:1], 0, s[72:73]
	s_lshl_b32 s72, s94, 1
	global_load_dwordx4 v[88:91], v[2:3], off offset:2048
	global_load_dwordx4 v[76:79], v[2:3], off offset:1024
	v_lshl_add_u64 v[2:3], v[0:1], 0, s[72:73]
	global_load_dwordx4 v[92:95], v[2:3], off offset:2048
	global_load_dwordx4 v[80:83], v[2:3], off offset:1024
	global_load_dwordx4 v[68:71], v[0:1], off offset:2048
	global_load_dwordx4 v[64:67], v[0:1], off offset:1024
	v_cndmask_b32_e32 v5, 0, v128, vcc
	v_sub_f32_e32 v2, v5, v4
	v_exp_f32_e32 v2, v2
	s_mov_b64 s[0:1], 0x800
	v_lshl_add_u64 v[106:107], v[0:1], 0, s[0:1]
	s_mov_b64 s[0:1], 0x400
	v_ldexp_f32 v2, v2, s79
	v_cvt_f32_ubyte0_e32 v3, s92
	v_mul_f32_e32 v2, 0x3fb8aa3b, v2
	v_lshl_add_u64 v[108:109], v[0:1], 0, s[0:1]
	s_mov_b32 s0, 2.0
	v_mul_f32_e32 v110, v2, v3
	s_mov_b32 s1, 0x40400000
	v_pk_mul_f32 v[112:113], v[110:111], s[0:1] op_sel_hi:[0,1]
	s_mov_b32 s0, 0x41000000
	s_mov_b32 s1, 0x41100000
	v_pk_mul_f32 v[114:115], v[110:111], s[0:1] op_sel_hi:[0,1]
	s_mov_b32 s0, 0x41200000
	s_mov_b32 s1, 0x41300000
	v_mul_f32_e32 v105, 0, v110
	v_pk_mul_f32 v[116:117], v[110:111], s[0:1] op_sel_hi:[0,1]
	v_pk_mul_f32 v[118:119], v[110:111], s[80:81] op_sel_hi:[0,1]
	v_pk_mul_f32 v[120:121], v[110:111], s[82:83] op_sel_hi:[0,1]
	v_pk_mul_f32 v[122:123], v[110:111], s[84:85] op_sel_hi:[0,1]
	v_pk_mul_f32 v[124:125], v[110:111], s[86:87] op_sel_hi:[0,1]
	v_subrev_u32_e32 v135, s90, v127
	s_lshl_b32 s72, s97, 1
	s_lshl_b32 s90, s94, 1
	s_lshl_b32 s92, s95, 1
	s_lshl_b32 s94, s96, 1
	v_mov_b32_e32 v134, v97
	v_mov_b32_e32 v16, v97
	v_mov_b32_e32 v17, v97
	v_mov_b32_e32 v18, v97
	v_mov_b32_e32 v19, v97
	v_mov_b32_e32 v20, v97
	v_mov_b32_e32 v21, v97
	v_mov_b32_e32 v22, v97
	v_mov_b32_e32 v23, v97
	v_mov_b32_e32 v24, v97
	v_mov_b32_e32 v25, v97
	v_mov_b32_e32 v26, v97
	v_mov_b32_e32 v27, v97
	v_mov_b32_e32 v28, v97
	v_mov_b32_e32 v29, v97
	v_mov_b32_e32 v30, v97
	v_mov_b32_e32 v31, v97
	v_mov_b32_e32 v0, v97
	v_mov_b32_e32 v1, v97
	v_mov_b32_e32 v2, v97
	v_mov_b32_e32 v3, v97
	v_mov_b32_e32 v4, v97
	v_mov_b32_e32 v5, v97
	v_mov_b32_e32 v6, v97
	v_mov_b32_e32 v7, v97
	v_mov_b32_e32 v8, v97
	v_mov_b32_e32 v9, v97
	v_mov_b32_e32 v10, v97
	v_mov_b32_e32 v11, v97
	v_mov_b32_e32 v12, v97
	v_mov_b32_e32 v13, v97
	v_mov_b32_e32 v14, v97
	v_mov_b32_e32 v15, v97

; #define LAS __attribute__((address_space(3)))
; __device__ __forceinline__ void mlstm_pass2(const bf16_t* PR, const bf16_t* QC, const float* gain, bf16_t* Y, LAS unsigned char* lds,
;                                             float* NB, const float* DEN, const float* BC, const float* FIMG, const float* DSEG, int st_first, int st_stride) {
;     ...
;         const size_t rs0 = (size_t)b * SEQL + 64 * (8 * seg);
;         const int frow = tid >> 4, fch = tid & 15;
;         const bf16_t* pQ = QC + (rs0 + frow) * 512 + hm * 128 + 8 * fch;
;         const int wq = (w < 4) ? w : 0;
;         const float* pN = num_ptr(NB, rs0 + r, hm) + 32 * wq + 4 * h;
;         const bf16_t* pO = PR + (rs0 + r) * PW + PC_OM + hm * 128 + 32 * wq + 4 * h;
;         const float* pB = BC + (rs0 + r) * 4 + hm; const float* pD = DEN + (rs0 + r) * 4 + hm;
;         f32x4 gv[4];
; #pragma unroll
;         for (int g4 = 0; g4 < 4; ++g4) gv[g4] = *(const f32x4*)(gain + hm * 128 + 32 * wq + 8 * g4 + 4 * h);
;         u32x4 fQ[2]; f32x4 nv[2][4]; u32x2 ov[2][4]; float bcv[2], dnv[2];
; #pragma unroll
;         for (int p2 = 0; p2 < 2; ++p2) fQ[p2] = *(const u32x4*)(pQ + (size_t)32 * p2 * 512);
; #pragma unroll
;         for (int tt = 0; tt < 2; ++tt) { bcv[tt] = pB[tt * 32 * 4]; dnv[tt] = pD[tt * 32 * 4];
; #pragma unroll
;             for (int g4 = 0; g4 < 4; ++g4) { nv[tt][g4] = *(const f32x4*)(pN + (size_t)tt * 32 * 512 + 8 * g4); ov[tt][g4] = *(const u32x2*)(pO + (size_t)tt * 32 * PW + 8 * g4); } }
;         for (int cc = 0; cc < 8; ++cc) {
;             const size_t r0 = rs0 + 64 * cc;
; #pragma unroll
;             for (int p2 = 0; p2 < 2; ++p2) *(LAS u32x4*)(lds + ML_QT + (frow + 32 * p2) * KROW + 16 * fch) = fQ[p2];
;             __syncthreads();
;             if (cc < 7) { pQ += 64 * 512;
; #pragma unroll
;                 for (int p2 = 0; p2 < 2; ++p2) fQ[p2] = *(const u32x4*)(pQ + (size_t)32 * p2 * 512); }
;             f32x16 res[2];
;             if (w < 5) {
; #pragma unroll
;                 for (int tt = 0; tt < 2; ++tt) {
;                     const LAS unsigned char* qb0 = lds + ML_QT + (32 * tt + r) * KROW + 8 * h;
;                     f32x16 acc;
; #pragma unroll
;                     for (int e = 0; e < 16; ++e) acc[e] = 0.f;
; #pragma unroll
;                     for (int i = 0; i < 4; ++i)
; #pragma unroll
.LBB0_570:
	s_and_b32 s54, s8, 3
	s_ashr_i32 s8, s51, 4
	s_ashr_i32 s9, s8, 31
	s_lshl_b64 s[0:1], s[8:9], 11
	s_lshl_b32 s2, s26, 9
	s_or_b32 s2, s0, s2
	s_mov_b32 s3, s1
	v_lshl_add_u64 v[0:1], s[2:3], 0, v[110:111]
	v_mov_b32_e32 v3, s1
	v_or_b32_e32 v2, s2, v104
	v_lshlrev_b64 v[0:1], 10, v[0:1]
	v_lshlrev_b64 v[4:5], 11, v[2:3]
	v_mov_b64_e32 v[6:7], s[10:11]
	v_lshl_add_u64 v[0:1], s[12:13], 0, v[0:1]
	s_lshl_b32 s26, s54, 8
	v_lshl_add_u64 v[4:5], s[14:15], 0, v[4:5]
	s_lshl_b32 s40, s54, 9
	s_mov_b32 s41, s27
	v_mad_u64_u32 v[6:7], s[52:53], v2, s44, v[6:7]
	v_lshl_add_u64 v[0:1], v[0:1], 0, s[26:27]
	v_lshl_add_u64 v[4:5], v[4:5], 0, s[40:41]
	v_mad_i32_i24 v7, s1, v193, v7
	v_lshl_add_u64 v[10:11], v[114:115], 0, s[40:41]
	v_lshl_add_u64 v[4:5], s[28:29], 2, v[4:5]
	v_lshl_add_u64 v[6:7], v[6:7], 0, s[26:27]
	global_load_dwordx4 v[60:63], v[10:11], off
	global_load_dwordx4 v[56:59], v[10:11], off offset:32
	global_load_dwordx4 v[52:55], v[10:11], off offset:64
	global_load_dwordx4 v[48:51], v[10:11], off offset:96
	v_lshl_add_u64 v[0:1], v[0:1], 0, v[106:107]
	v_lshlrev_b32_e32 v10, 2, v112
	v_mov_b32_e32 v11, v107
	v_lshl_add_u64 v[6:7], s[28:29], 1, v[6:7]
	v_lshl_add_u64 v[4:5], v[4:5], 0, v[10:11]
	global_load_dwordx4 v[80:83], v[0:1], off
	v_add_co_u32_e32 v0, vcc, s45, v0
	v_lshlrev_b32_e32 v10, 1, v112
	s_nop 0
	v_addc_co_u32_e32 v1, vcc, 0, v1, vcc
	v_lshl_add_u64 v[6:7], v[6:7], 0, v[10:11]
	v_lshlrev_b64 v[2:3], 4, v[2:3]
	v_add_co_u32_e32 v12, vcc, s46, v6
	v_lshl_add_u64 v[8:9], s[16:17], 0, v[2:3]
	v_lshl_add_u64 v[2:3], s[18:19], 0, v[2:3]
	s_lshl_b32 s52, s54, 2
	s_mov_b32 s53, s27
	v_addc_co_u32_e32 v13, vcc, 0, v7, vcc
	v_lshl_add_u64 v[2:3], v[2:3], 0, s[52:53]
	v_lshl_add_u64 v[10:11], v[6:7], 0, s[30:31]
	v_lshl_add_u64 v[8:9], v[8:9], 0, s[52:53]
	global_load_dwordx2 v[186:187], v[12:13], off offset:2048
	global_load_dwordx4 v[100:103], v[4:5], off
	global_load_dwordx4 v[96:99], v[4:5], off offset:32
	global_load_dwordx4 v[92:95], v[4:5], off offset:64
	global_load_dwordx4 v[88:91], v[4:5], off offset:96
	global_load_dword v198, v[8:9], off
	global_load_dwordx2 v[172:173], v[10:11], off offset:32
	global_load_dword v196, v[8:9], off offset:512
	global_load_dwordx2 v[170:171], v[10:11], off offset:48
	global_load_dwordx4 v[84:87], v[0:1], off
	global_load_dword v188, v[2:3], off
	global_load_dwordx2 v[174:175], v[10:11], off offset:16
	global_load_dword v197, v[2:3], off offset:512
	v_add_co_u32_e32 v0, vcc, s47, v4
	s_and_b32 s41, s50, 3
	s_nop 0
	v_addc_co_u32_e32 v1, vcc, 0, v5, vcc
	v_add_co_u32_e32 v2, vcc, s48, v6
	s_lshl_b32 s53, s41, 9
	s_nop 0
	v_addc_co_u32_e32 v3, vcc, 0, v7, vcc
	global_load_dwordx4 v[76:79], v[0:1], off
	global_load_dwordx4 v[72:75], v[0:1], off offset:32
	global_load_dwordx4 v[68:71], v[0:1], off offset:64
	global_load_dwordx4 v[64:67], v[0:1], off offset:96
	global_load_dwordx2 v[168:169], v[2:3], off offset:2048
	global_load_dwordx2 v[166:167], v[2:3], off offset:2064
	global_load_dwordx2 v[164:165], v[2:3], off offset:2080
	global_load_dwordx2 v[162:163], v[2:3], off offset:2096
	s_lshl_b32 s54, s54, 7
	v_add_u32_e32 v160, s54, v119
	s_or_b32 s54, s0, s53
	s_mov_b32 s55, s1
	v_lshl_add_u64 v[0:1], s[54:55], 0, v[110:111]
	s_lshl_b32 s41, s41, 20
	v_lshlrev_b64 v[176:177], 10, v[0:1]
	s_lshl_b64 s[8:9], s[8:9], 22
	v_or_b32_e32 v0, v116, v176
	s_or_b32 s8, s8, s41
	v_ashrrev_i32_e32 v161, 31, v160
	v_or_b32_e32 v176, s26, v0
	v_mov_b32_e32 v0, s8
	v_mov_b32_e32 v1, s9
	v_lshl_add_u64 v[0:1], v[160:161], 1, v[0:1]
	v_lshl_add_u64 v[178:179], v[122:123], 0, v[0:1]
	v_or_b32_e32 v0, s0, v104
	v_mov_b32_e32 v1, s1
	v_or_b32_e32 v0, s53, v0
	v_lshlrev_b64 v[2:3], 11, v[0:1]
	v_lshlrev_b64 v[182:183], 4, v[0:1]
	v_mad_u64_u32 v[0:1], s[8:9], v0, s44, v[126:127]
	v_or_b32_e32 v2, s40, v2
	v_mad_i32_i24 v1, s1, v193, v1
	v_lshl_add_u64 v[180:181], v[124:125], 0, v[2:3]
	v_or_b32_e32 v182, s52, v182
	v_lshl_add_u64 v[184:185], v[0:1], 0, s[26:27]
	s_mov_b64 s[0:1], 0
	s_waitcnt vmcnt(0)
	s_branch .LBB0_572
.Lp2_nostore:
	s_waitcnt vmcnt(0)
.LBB0_571:
	s_add_u32 s0, s0, 0x20000
	s_addc_u32 s1, s1, 0
	v_lshl_add_u64 v[176:177], v[176:177], 0, s[34:35]
	v_lshl_add_u64 v[182:183], v[182:183], 0, s[36:37]
	s_cmp_eq_u32 s0, 0xe0000
	v_lshl_add_u64 v[184:185], v[184:185], 0, s[38:39]
	s_cbranch_scc1 .LBB0_593
.LBB0_572:
	v_lshl_add_u64 v[0:1], s[10:11], 0, v[176:177]
	v_add_co_u32_e32 v2, vcc, 0x19310000, v0
	s_waitcnt vmcnt(8) lgkmcnt(0)
	ds_write_b128 v194, v[80:83]
	ds_write_b128 v194, v[84:87] offset:8704
	v_addc_co_u32_e32 v3, vcc, 0, v1, vcc
	v_add_co_u32_e32 v0, vcc, 0x19318000, v0
	s_waitcnt lgkmcnt(0)
	s_barrier
	v_addc_co_u32_e32 v1, vcc, 0, v1, vcc
	global_load_dwordx4 v[80:83], v[2:3], off
	global_load_dwordx4 v[84:87], v[0:1], off
	s_and_b64 vcc, exec, s[6:7]
	s_cbranch_vccnz .LBB0_585
	v_add_u32_e32 v199, v113, v121
	ds_read2_b64 v[0:3], v199 offset1:2
	ds_read2_b64 v[200:203], v199 offset0:4 offset1:6
	v_mul_f32_e32 v188, 0x3fb8aa3b, v188
	v_exp_f32_e32 v188, v188
	s_mov_b64 s[8:9], -1
	s_waitcnt lgkmcnt(0)
	v_mfma_f32_32x32x16_bf16 v[0:15], v[16:19], v[0:3], 0
	s_and_b64 vcc, exec, s[22:23]
	v_mfma_f32_32x32x16_bf16 v[0:15], v[20:23], v[200:203], v[0:15]
	ds_read2_b64 v[200:203], v199 offset0:8 offset1:10
	s_waitcnt lgkmcnt(0)
	v_mfma_f32_32x32x16_bf16 v[0:15], v[24:27], v[200:203], v[0:15]
	ds_read2_b64 v[200:203], v199 offset0:12 offset1:14
	s_waitcnt lgkmcnt(0)
	v_mfma_f32_32x32x16_bf16 v[0:15], v[28:31], v[200:203], v[0:15]
	ds_read2_b64 v[200:203], v199 offset0:16 offset1:18
	s_waitcnt lgkmcnt(0)
	v_mfma_f32_32x32x16_bf16 v[0:15], v[32:35], v[200:203], v[0:15]
	ds_read2_b64 v[200:203], v199 offset0:20 offset1:22
	s_waitcnt lgkmcnt(0)
	v_mfma_f32_32x32x16_bf16 v[0:15], v[36:39], v[200:203], v[0:15]
	ds_read2_b64 v[200:203], v199 offset0:24 offset1:26
	s_waitcnt lgkmcnt(0)
	v_mfma_f32_32x32x16_bf16 v[0:15], v[40:43], v[200:203], v[0:15]
	ds_read2_b64 v[200:203], v199 offset0:28 offset1:30
	s_waitcnt lgkmcnt(0)
	v_mfma_f32_32x32x16_bf16 v[0:15], v[44:47], v[200:203], v[0:15]
	s_cbranch_vccz .LBB0_577
	s_and_saveexec_b64 s[8:9], s[4:5]
	s_nop 9
	v_fmac_f32_e32 v198, v188, v0
	ds_write_b32 v105, v198 offset:62720
	s_or_b64 exec, exec, s[8:9]
	s_mov_b64 s[8:9], 0

; #define LAS __attribute__((address_space(3)))
; #define LFENCE() asm volatile("" ::: "memory")
; template <int MODE> ...
;     const int r = lane & 31, h = lane >> 5, li = lane & 15, gg = (lane >> 4) & 1;
;     const size_t seqrow0 = (size_t)b * SEQL + res;
;     const int q0 = 32 * qt;
;     const size_t rstride = (size_t)dil * PW;
;     bf16x8 qf[4];
;     { const bf16_t* qp = PR + (seqrow0 + (size_t)(q0 + r) * dil) * PW + PC_QA + head * 64 + 8 * h;
; #pragma unroll
;       for (int s = 0; s < 4; ++s) qf[s] = *(const bf16x8*)(qp + 16 * s); }
;     f32x16 o[2];
; #pragma unroll
;     for (int dt = 0; dt < 2; ++dt)
; #pragma unroll
;         for (int i = 0; i < 16; ++i) o[dt][i] = 0.f;
;     float l = 0.f;
;     const float slope = exp2f(-(float)(head + 1)) * LOG2E * (float)dil;
;     const LAS unsigned char* trb = vl + (4 * h + (li >> 2)) * VROW + (16 * gg + 4 * (li & 3)) * 2;
;     const int first = (q0 >= 128) ? 0 : ((128 - q0) >> 5);
;     const size_t prow = (seqrow0 + (size_t)(q0 - 128 + 32 * first + (lane >> 3)) * dil) * PW + head * 64 + 8 * (lane & 7);
;     const bf16_t* kp = PR + prow + PC_KA; const bf16_t* vp = PR + prow + PC_VA;
;     LAS unsigned char* kl = vl + 4608;
;     const int stoff = (lane >> 3) * VROW + 16 * (lane & 7);
;     u32x4 kn[4], vn[4];
; #pragma unroll
;     for (int i = 0; i < 4; ++i) { kn[i] = *(const u32x4*)(kp + (size_t)(8 * i) * rstride); vn[i] = *(const u32x4*)(vp + (size_t)(8 * i) * rstride); }
;     const int rr = r - 4 * h;
; #pragma unroll 1
;     for (int kt = first; kt < 5; ++kt) {
; #pragma unroll
;         for (int i = 0; i < 4; ++i) { *(LAS u32x4*)(kl + stoff + 8 * i * VROW) = kn[i]; *(LAS u32x4*)(vl + stoff + 8 * i * VROW) = vn[i]; }
;         LFENCE();
;         if (kt < 4) {
;             kp += 32 * rstride; vp += 32 * rstride;
; #pragma unroll
;             for (int i = 0; i < 4; ++i) { kn[i] = *(const u32x4*)(kp + (size_t)(8 * i) * rstride); vn[i] = *(const u32x4*)(vp + (size_t)(8 * i) * rstride); }
;         }
;         const float fb = slope * (float)(rr + 128 - 32 * kt);
;         f32x16 s;
; #pragma unroll
;         for (int i = 0; i < 16; ++i) s[i] = slope * (float)((i & 3) + 8 * (i >> 2)) - fb;
; __global__ void __launch_bounds__(512, 2) mega(Args a) {
;     ...
;         for (int task = bx * 8 + wave; task < 8192; task += G * 8) { const int bh = task >> 6, wq = task & 63;
.LBB0_618:
	s_bfe_u32 s91, s33, 0x60006
	s_bfe_u32 s0, s33, 0x30003
	s_bfe_u32 s98, s33, 0x1000c
	s_lshl_b32 s98, s98, 3
	s_or_b32 s0, s0, s98
	s_ashr_i32 s1, s0, 31
	s_lshl_b32 s86, s91, 5
	s_lshl_b64 s[0:1], s[0:1], 11
	v_or_b32_e32 v0, s86, v99
	v_or_b32_e32 v106, s0, v0
	s_movk_i32 s78, 0x1c00
	s_and_b32 s90, s33, 7
	v_mad_u64_u32 v[0:1], s[2:3], v106, s78, v[102:103]
	s_add_i32 s2, s90, 1
	s_nop 0
	v_cvt_f32_ubyte0_e32 v4, s2
	s_mov_b32 s2, 0x42fc0000
	s_lshl_b32 s83, s90, 6
	s_lshl_b32 s76, s90, 7
	v_cmp_lt_f32_e32 vcc, s2, v4
	s_and_b64 s[2:3], vcc, exec
	s_cselect_b32 s87, 0xffffffc0, 0
	s_sub_i32 s2, 0x80, s86
	s_ashr_i32 s2, s2, 5
	s_cmp_lt_u32 s91, 4
	v_mad_i32_i24 v1, s1, v128, v1
	s_cselect_b32 s91, s2, 0
	v_lshl_add_u64 v[0:1], v[0:1], 0, s[76:77]
	s_lshl_b32 s88, s91, 5
	v_lshl_add_u64 v[0:1], v[0:1], 0, v[104:105]
	s_add_i32 s2, s88, s86
	global_load_dwordx4 v[48:51], v[0:1], off
	global_load_dwordx4 v[52:55], v[0:1], off offset:32
	global_load_dwordx4 v[56:59], v[0:1], off offset:64
	global_load_dwordx4 v[60:63], v[0:1], off offset:96
	v_add_u32_e32 v0, s2, v126
	v_ashrrev_i32_e32 v1, 31, v0
	v_lshl_add_u64 v[0:1], s[0:1], 0, v[0:1]
	v_mad_u64_u32 v[2:3], s[2:3], v0, s78, v[100:101]
	v_mad_i32_i24 v3, v1, s78, v3
	v_lshl_add_u64 v[0:1], v[2:3], 0, s[76:77]
	s_mov_b32 s0, 0x2a000
	v_cndmask_b32_e32 v5, 0, v129, vcc
	v_add_co_u32_e32 v2, vcc, s0, v0
	s_mov_b32 s0, 0x1c000
	s_nop 0
	v_addc_co_u32_e32 v3, vcc, 0, v1, vcc
	global_load_dwordx4 v[92:95], v[2:3], off offset:2048
	global_load_dwordx4 v[88:91], v[2:3], off offset:1024
	v_add_co_u32_e32 v2, vcc, s0, v0
	s_mov_b32 s0, 0xe000
	s_nop 0
	v_addc_co_u32_e32 v3, vcc, 0, v1, vcc
	global_load_dwordx4 v[84:87], v[2:3], off offset:2048
	global_load_dwordx4 v[80:83], v[2:3], off offset:1024
	v_add_co_u32_e32 v2, vcc, s0, v0
	v_mov_b32_e32 v107, s1
	s_nop 0
	v_addc_co_u32_e32 v3, vcc, 0, v1, vcc
	global_load_dwordx4 v[76:79], v[2:3], off offset:2048
	global_load_dwordx4 v[72:75], v[2:3], off offset:1024
	global_load_dwordx4 v[68:71], v[0:1], off offset:2048
	global_load_dwordx4 v[64:67], v[0:1], off offset:1024
	v_sub_f32_e32 v2, v5, v4
	v_exp_f32_e32 v2, v2
	s_mov_b64 s[0:1], 0x800
	v_lshl_add_u64 v[112:113], v[0:1], 0, s[0:1]
	s_mov_b64 s[0:1], 0x400
	v_ldexp_f32 v2, v2, s87
	v_lshl_add_u64 v[118:119], v[0:1], 0, s[0:1]
	s_mov_b32 s0, 2.0
	v_mul_f32_e32 v96, 0x3fb8aa3b, v2
	s_mov_b32 s1, 0x40400000
	v_pk_mul_f32 v[108:109], v[96:97], s[0:1] op_sel_hi:[0,1]
	s_mov_b32 s0, 0x41000000
	s_mov_b32 s1, 0x41100000
	v_pk_mul_f32 v[110:111], v[96:97], s[0:1] op_sel_hi:[0,1]
	s_mov_b32 s0, 0x41200000
	s_mov_b32 s1, 0x41300000
	v_pk_mul_f32 v[114:115], v[96:97], s[0:1] op_sel_hi:[0,1]
	s_mov_b32 s0, 0x41800000
	s_mov_b32 s1, 0x41880000
	v_pk_mul_f32 v[116:117], v[96:97], s[0:1] op_sel_hi:[0,1]
	s_mov_b32 s0, 0x41900000
	s_mov_b32 s1, 0x41980000
	v_pk_mul_f32 v[120:121], v[96:97], s[0:1] op_sel_hi:[0,1]
	s_mov_b32 s0, 0x41c00000
	s_mov_b32 s1, 0x41c80000
	v_mul_f32_e32 v136, 0, v96
	v_pk_mul_f32 v[122:123], v[96:97], s[0:1] op_sel_hi:[0,1]
	v_pk_mul_f32 v[124:125], v[96:97], s[96:97] op_sel_hi:[0,1]
	v_subrev_u32_e32 v137, s88, v127
	v_mov_b32_e32 v138, 0
	v_mov_b32_e32 v16, 0
	v_mov_b32_e32 v17, v97
	v_mov_b32_e32 v18, v97
	v_mov_b32_e32 v19, v97
	v_mov_b32_e32 v20, v97
	v_mov_b32_e32 v21, v97
	v_mov_b32_e32 v22, v97
	v_mov_b32_e32 v23, v97
	v_mov_b32_e32 v24, v97
	v_mov_b32_e32 v25, v97
	v_mov_b32_e32 v26, v97
	v_mov_b32_e32 v27, v97
	v_mov_b32_e32 v28, v97
	v_mov_b32_e32 v29, v97
	v_mov_b32_e32 v30, v97
	v_mov_b32_e32 v31, v97
	v_mov_b32_e32 v0, 0
	v_mov_b32_e32 v1, v97
	v_mov_b32_e32 v2, v97
	v_mov_b32_e32 v3, v97
	v_mov_b32_e32 v4, v97
	v_mov_b32_e32 v5, v97
	v_mov_b32_e32 v6, v97
	v_mov_b32_e32 v7, v97
	v_mov_b32_e32 v8, v97
	v_mov_b32_e32 v9, v97
	v_mov_b32_e32 v10, v97
	v_mov_b32_e32 v11, v97
	v_mov_b32_e32 v12, v97
	v_mov_b32_e32 v13, v97
	v_mov_b32_e32 v14, v97
	v_mov_b32_e32 v15, v97

; #define LAS __attribute__((address_space(3)))
; __global__ void __launch_bounds__(512, 2) mega(Args a) {
;     extern __shared__ __attribute__((aligned(16))) unsigned char lds_raw[];
;     LAS unsigned char* lds = (LAS unsigned char*)lds_raw;
	.amdhsa_kernel _Z4mega4Args
		.amdhsa_group_segment_fixed_size 0
		.amdhsa_private_segment_fixed_size 0
		.amdhsa_kernarg_size 432
		.amdhsa_user_sgpr_count 2
		.amdhsa_user_sgpr_dispatch_ptr 0
		.amdhsa_user_sgpr_queue_ptr 0
		.amdhsa_user_sgpr_kernarg_segment_ptr 1
		.amdhsa_user_sgpr_dispatch_id 0
		.amdhsa_user_sgpr_kernarg_preload_length 0
		.amdhsa_user_sgpr_kernarg_preload_offset 0
		.amdhsa_user_sgpr_private_segment_size 0
		.amdhsa_uses_dynamic_stack 0
		.amdhsa_enable_private_segment 0
		.amdhsa_system_sgpr_workgroup_id_x 1
		.amdhsa_system_sgpr_workgroup_id_y 0
		.amdhsa_system_sgpr_workgroup_id_z 0
		.amdhsa_system_sgpr_workgroup_info 0
		.amdhsa_system_vgpr_workitem_id 2
		.amdhsa_next_free_vgpr 254
		.amdhsa_next_free_sgpr 102
		.amdhsa_accum_offset 256
		.amdhsa_reserve_vcc 1
		.amdhsa_float_round_mode_32 0
		.amdhsa_float_round_mode_16_64 0
		.amdhsa_float_denorm_mode_32 3
		.amdhsa_float_denorm_mode_16_64 3
		.amdhsa_dx10_clamp 1
		.amdhsa_ieee_mode 1
		.amdhsa_fp16_overflow 0
		.amdhsa_tg_split 0
		.amdhsa_exception_fp_ieee_invalid_op 0
		.amdhsa_exception_fp_denorm_src 0
		.amdhsa_exception_fp_ieee_div_zero 0
		.amdhsa_exception_fp_ieee_overflow 0
		.amdhsa_exception_fp_ieee_underflow 0
		.amdhsa_exception_fp_ieee_inexact 0
		.amdhsa_exception_int_div_zero 0
	.end_amdhsa_kernel

amdhsa.kernels:
  - .agpr_count:     0
    .args:
      - .offset:         0
        .size:           176
        .value_kind:     by_value
      - .offset:         176
        .size:           4
        .value_kind:     hidden_block_count_x
      - .offset:         180
        .size:           4
        .value_kind:     hidden_block_count_y
      - .offset:         184
        .size:           4
        .value_kind:     hidden_block_count_z
      - .offset:         188
        .size:           2
        .value_kind:     hidden_group_size_x
      - .offset:         190
        .size:           2
        .value_kind:     hidden_group_size_y
      - .offset:         192
        .size:           2
        .value_kind:     hidden_group_size_z
      - .offset:         194
        .size:           2
        .value_kind:     hidden_remainder_x
      - .offset:         196
        .size:           2
        .value_kind:     hidden_remainder_y
      - .offset:         198
        .size:           2
        .value_kind:     hidden_remainder_z
      - .offset:         216
        .size:           8
        .value_kind:     hidden_global_offset_x
      - .offset:         224
        .size:           8
        .value_kind:     hidden_global_offset_y
      - .offset:         232
        .size:           8
        .value_kind:     hidden_global_offset_z
      - .offset:         240
        .size:           2
        .value_kind:     hidden_grid_dims
      - .offset:         264
        .size:           8
        .value_kind:     hidden_multigrid_sync_arg
      - .offset:         296
        .size:           4
        .value_kind:     hidden_dynamic_lds_size
    .group_segment_fixed_size: 0
    .kernarg_segment_align: 8
    .kernarg_segment_size: 432
    .language:       OpenCL C
    .language_version:
      - 2
      - 0
    .max_flat_workgroup_size: 512
    .name:           _Z4mega4Args
    .private_segment_fixed_size: 0
    .sgpr_count:     108
    .sgpr_spill_count: 86
    .symbol:         _Z4mega4Args.kd
    .uniform_work_group_size: 1
    .uses_dynamic_stack: false
    .vgpr_count:     254
    .vgpr_spill_count: 0
    .wavefront_size: 64
